# merge epilogue: gated sum of the three branches kept in the f32 MFMA accumulators (clamped gate ratios), only the last branch stores the bf16 merged tile
# speedup vs baseline: 1.0776x; 1.0054x over previous
; #define PG8_STAGE(bufoff, gbase, voff) do { _Pragma("unroll") for (int _i = 0; _i < 2; ++_i) \
;         __builtin_amdgcn_global_load_lds((const unsigned*)((const char*)(gbase) + (voff)[_i]), (PG8_LAS unsigned*)(lds + (bufoff) + ldsw + _i * 8192), 16, 0, 0); } while (0)
; #define PG8_LDA(dst, b, h) do { _Pragma("unroll") for (int m = 0; m < 4; ++m) _Pragma("unroll") for (int k = 0; k < 2; ++k) dst[m][k] = *(const PG8_LAS bf16x8*)(lds + PG8_SA(b, h) + aoff + m * 2048 + k * 1024); } while (0)
; #define PG8_LDB(dst, b, h) do { _Pragma("unroll") for (int n = 0; n < 2; ++n) _Pragma("unroll") for (int k = 0; k < 2; ++k) dst[n][k] = *(const PG8_LAS bf16x8*)(lds + PG8_SB(b, h) + boff + n * 2048 + k * 1024); } while (0)
; #define PG8_WAIT_V(n) asm volatile("s_waitcnt vmcnt(" #n ")" ::: "memory")
; #define PG8_WAIT_L(n) asm volatile("s_waitcnt lgkmcnt(" #n ")" ::: "memory")
; #define PG8_BAR __builtin_amdgcn_s_barrier()
; template <class Epi, class Sched, bool ALIGN_EPI = false, bool SP2 = false>
; __device__ __forceinline__ void gemm_phase(PG8_LAS unsigned char* lds, const Gemm g, const Sched& S, const Epi& E, const int tid_in) {
;     ...
;         const char* nA = has_next ? (const char*)g.A + (size_t)nxt.pm * tstepA + (size_t)nxt.k0 * 2 : cA; const char* nB = has_next ? (const char*)g.Bt + (size_t)nxt.pn * tstepB + (size_t)nxt.k0 * 2 : cB;
;         for (int t = 0; t < nt; t += 2) {
;             const bool last = (t == nt - 2);
;             const char* a1 = cA + (size_t)(t + 1) * kstep;
;             const char* a2 = last ? nA : cA + (size_t)(t + 2) * kstep; const char* b2 = last ? nB : cB + (size_t)(t + 2) * kstep;
;             const char* a3 = a2 + kstep; const char* b3 = b2 + kstep;
;             if (last && has_next) S.a_ready(nxt);
;             if constexpr (SP2) {
;             PG8_LDB(B0, 0, 0); PG8_LDB(B1, 0, 1); PG8_SCHED; PG8_LDA(At, 0, 0); PG8_STAGE(PG8_SA(1, 1), a1 + hstepA, voffA);
;             PG8_WAIT_V(8); PG8_WAIT_L(0); PG8_BAR; PG8_MMA(0, 0, At, B0); PG8_MMA(0, 1, At, B1); PG8_BAR; PG8_SCHED;
;     ...
; #pragma unroll
;         for (int a = 0; a < 2; ++a)
; #pragma unroll
;             for (int b = 0; b < 2; ++b)
; #pragma unroll
;                 for (int m = 0; m < 4; ++m)
; #pragma unroll
;                     for (int n = 0; n < 2; ++n) acc[a][b][m][n] = (f32x4){0.f, 0.f, 0.f, 0.f};
;         cur = nxt; cA = nA; cB = nB; ++ui;
.LBB0_292:
	s_ashr_i32 s11, s10, 31
	s_lshl_b64 s[14:15], s[10:11], 18
	s_add_u32 s14, s33, s14
	s_addc_u32 s15, s39, s15
	s_and_b64 s[18:19], s[16:17], exec
	s_cselect_b32 s7, s15, s21
	s_cselect_b32 s11, s14, s20
	s_ashr_i32 s13, s12, 31
	s_lshl_b64 s[18:19], s[12:13], 18
	s_add_u32 s18, s40, s18
	s_addc_u32 s19, s41, s19
	s_and_b64 s[28:29], s[16:17], exec
	s_cselect_b32 s13, s19, s23
	s_cselect_b32 s56, s18, s22
	s_add_u32 s20, s20, 0x20080
	s_addc_u32 s21, s21, 0
	s_add_u32 s60, s22, 0x100
	s_addc_u32 s70, s23, 0
	s_mov_b32 s71, -2
	s_cmpk_ge_i32 s6, 0x42
	s_cbranch_scc1 .Lmz_keep
	v_mov_b32_e32 v0, 0
	v_mov_b32_e32 v1, v0
	v_mov_b32_e32 v2, v0
	v_mov_b32_e32 v3, v0
	v_mov_b32_e32 v4, v0
	v_mov_b32_e32 v5, v0
	v_mov_b32_e32 v6, v0
	v_mov_b32_e32 v7, v0
	v_mov_b32_e32 v16, v0
	v_mov_b32_e32 v17, v0
	v_mov_b32_e32 v18, v0
	v_mov_b32_e32 v19, v0
	v_mov_b32_e32 v20, v0
	v_mov_b32_e32 v21, v0
	v_mov_b32_e32 v22, v0
	v_mov_b32_e32 v23, v0
	v_mov_b32_e32 v32, v0
	v_mov_b32_e32 v33, v0
	v_mov_b32_e32 v34, v0
	v_mov_b32_e32 v35, v0
	v_mov_b32_e32 v36, v0
	v_mov_b32_e32 v37, v0
	v_mov_b32_e32 v38, v0
	v_mov_b32_e32 v39, v0
	v_mov_b32_e32 v48, v0
	v_mov_b32_e32 v49, v0
	v_mov_b32_e32 v50, v0
	v_mov_b32_e32 v51, v0
	v_mov_b32_e32 v52, v0
	v_mov_b32_e32 v53, v0
	v_mov_b32_e32 v54, v0
	v_mov_b32_e32 v55, v0
	v_mov_b32_e32 v8, v0
	v_mov_b32_e32 v9, v0
	v_mov_b32_e32 v10, v0
	v_mov_b32_e32 v11, v0
	v_mov_b32_e32 v12, v0
	v_mov_b32_e32 v13, v0
	v_mov_b32_e32 v14, v0
	v_mov_b32_e32 v15, v0
	v_mov_b32_e32 v24, v0
	v_mov_b32_e32 v25, v0
	v_mov_b32_e32 v26, v0
	v_mov_b32_e32 v27, v0
	v_mov_b32_e32 v28, v0
	v_mov_b32_e32 v29, v0
	v_mov_b32_e32 v30, v0
	v_mov_b32_e32 v31, v0
	v_mov_b32_e32 v40, v0
	v_mov_b32_e32 v41, v0
	v_mov_b32_e32 v42, v0
	v_mov_b32_e32 v43, v0
	v_mov_b32_e32 v44, v0
	v_mov_b32_e32 v45, v0
	v_mov_b32_e32 v46, v0
	v_mov_b32_e32 v47, v0
	v_mov_b32_e32 v56, v0
	v_mov_b32_e32 v57, v0
	v_mov_b32_e32 v58, v0
	v_mov_b32_e32 v59, v0
	v_mov_b32_e32 v60, v0
	v_mov_b32_e32 v61, v0
	v_mov_b32_e32 v62, v0
	v_mov_b32_e32 v63, v0
	v_mov_b32_e32 v64, v0
	v_mov_b32_e32 v65, v0
	v_mov_b32_e32 v66, v0
	v_mov_b32_e32 v67, v0
	v_mov_b32_e32 v68, v0
	v_mov_b32_e32 v69, v0
	v_mov_b32_e32 v70, v0
	v_mov_b32_e32 v71, v0
	v_mov_b32_e32 v80, v0
	v_mov_b32_e32 v81, v0
	v_mov_b32_e32 v82, v0
	v_mov_b32_e32 v83, v0
	v_mov_b32_e32 v84, v0
	v_mov_b32_e32 v85, v0
	v_mov_b32_e32 v86, v0
	v_mov_b32_e32 v87, v0
	v_mov_b32_e32 v98, v0
	v_mov_b32_e32 v99, v0
	v_mov_b32_e32 v100, v0
	v_mov_b32_e32 v101, v0
	v_mov_b32_e32 v102, v0
	v_mov_b32_e32 v103, v0
	v_mov_b32_e32 v104, v0
	v_mov_b32_e32 v105, v0
	v_mov_b32_e32 v114, v0
	v_mov_b32_e32 v115, v0
	v_mov_b32_e32 v116, v0
	v_mov_b32_e32 v117, v0
	v_mov_b32_e32 v118, v0
	v_mov_b32_e32 v119, v0
	v_mov_b32_e32 v120, v0
	v_mov_b32_e32 v121, v0
	v_mov_b32_e32 v72, v0
	v_mov_b32_e32 v73, v0
	v_mov_b32_e32 v74, v0
	v_mov_b32_e32 v75, v0
	v_mov_b32_e32 v76, v0
	v_mov_b32_e32 v77, v0
	v_mov_b32_e32 v78, v0
	v_mov_b32_e32 v79, v0
	v_mov_b32_e32 v88, v0
	v_mov_b32_e32 v89, v0
	v_mov_b32_e32 v90, v0
	v_mov_b32_e32 v91, v0
	v_mov_b32_e32 v92, v0
	v_mov_b32_e32 v93, v0
	v_mov_b32_e32 v94, v0
	v_mov_b32_e32 v95, v0
	v_mov_b32_e32 v106, v0
	v_mov_b32_e32 v107, v0
	v_mov_b32_e32 v108, v0
	v_mov_b32_e32 v109, v0
	v_mov_b32_e32 v110, v0
	v_mov_b32_e32 v111, v0
	v_mov_b32_e32 v112, v0
	v_mov_b32_e32 v113, v0
	v_mov_b32_e32 v122, v0
	v_mov_b32_e32 v123, v0
	v_mov_b32_e32 v124, v0
	v_mov_b32_e32 v125, v0
	v_mov_b32_e32 v126, v0
	v_mov_b32_e32 v127, v0
	v_mov_b32_e32 v128, v0
	v_mov_b32_e32 v129, v0
.Lmz_keep:
.LBB0_293:
	s_add_u32 s22, s20, 0xfffe0080
	s_addc_u32 s23, s21, -1
	s_add_i32 s46, 0, 0x10000
	s_cmp_eq_u32 s71, 4
	s_cselect_b32 s29, s7, s23
	s_cselect_b32 s28, s11, s22
	v_add_u32_e32 v96, s46, v159
	s_cselect_b32 s23, s13, s70
	s_cselect_b32 s22, s56, s60
	s_add_i32 s74, 0, 0x14000
	ds_read_b128 v[142:145], v96
	ds_read_b128 v[150:153], v96 offset:1024
	ds_read_b128 v[154:157], v96 offset:2048
	ds_read_b128 v[162:165], v96 offset:3072
	v_add_u32_e32 v96, s74, v159
	ds_read_b128 v[166:169], v96
	ds_read_b128 v[170:173], v96 offset:1024
	ds_read_b128 v[174:177], v96 offset:2048
	ds_read_b128 v[178:181], v96 offset:3072
	v_lshl_add_u64 v[146:147], s[20:21], 0, v[138:139]
	s_add_i32 m0, s31, 0xc000
	ds_read_b128 v[182:185], v161
	ds_read_b128 v[186:189], v161 offset:1024
	ds_read_b128 v[202:205], v161 offset:2048
	ds_read_b128 v[206:209], v161 offset:3072
	ds_read_b128 v[210:213], v161 offset:4096
	ds_read_b128 v[214:217], v161 offset:5120
	ds_read_b128 v[218:221], v161 offset:6144
	ds_read_b128 v[222:225], v161 offset:7168
	global_load_lds_dwordx4 v[146:147], off
	v_lshl_add_u64 v[146:147], s[20:21], 0, v[140:141]
	s_add_i32 m0, s31, 0xe000
	s_nop 0
	global_load_lds_dwordx4 v[146:147], off
	s_waitcnt vmcnt(8)
	s_waitcnt lgkmcnt(0)
	s_barrier
; #define PG8_STAGE(bufoff, gbase, voff) do { _Pragma("unroll") for (int _i = 0; _i < 2; ++_i) \
;         __builtin_amdgcn_global_load_lds((const unsigned*)((const char*)(gbase) + (voff)[_i]), (PG8_LAS unsigned*)(lds + (bufoff) + ldsw + _i * 8192), 16, 0, 0); } while (0)
; #define PG8_LDA(dst, b, h) do { _Pragma("unroll") for (int m = 0; m < 4; ++m) _Pragma("unroll") for (int k = 0; k < 2; ++k) dst[m][k] = *(const PG8_LAS bf16x8*)(lds + PG8_SA(b, h) + aoff + m * 2048 + k * 1024); } while (0)
; #define PG8_LDB(dst, b, h) do { _Pragma("unroll") for (int n = 0; n < 2; ++n) _Pragma("unroll") for (int k = 0; k < 2; ++k) dst[n][k] = *(const PG8_LAS bf16x8*)(lds + PG8_SB(b, h) + boff + n * 2048 + k * 1024); } while (0)
; #define PG8_MMA(ai, bj, At, Bt) do { __builtin_amdgcn_s_setprio(1); _Pragma("unroll") for (int m = 0; m < 4; ++m) _Pragma("unroll") for (int n = 0; n < 2; ++n) _Pragma("unroll") for (int k = 0; k < 2; ++k) \
;         acc[ai][bj][m][n] = __builtin_amdgcn_mfma_f32_16x16x32_bf16(Bt[n][k], At[m][k], acc[ai][bj][m][n], 0, 0, 0); __builtin_amdgcn_s_setprio(0); } while (0)
; #define PG8_WAIT_V(n) asm volatile("s_waitcnt vmcnt(" #n ")" ::: "memory")
; #define PG8_WAIT_L(n) asm volatile("s_waitcnt lgkmcnt(" #n ")" ::: "memory")
; #define PG8_BAR __builtin_amdgcn_s_barrier()
; #define PG8_SCHED __builtin_amdgcn_sched_barrier(0)
; template <class Epi, class Sched, bool ALIGN_EPI = false, bool SP2 = false>
; __device__ __forceinline__ void gemm_phase(PG8_LAS unsigned char* lds, const Gemm g, const Sched& S, const Epi& E, const int tid_in) {
;     ...
;             PG8_LDB(B0, 0, 0); PG8_LDB(B1, 0, 1); PG8_SCHED; PG8_LDA(At, 0, 0); PG8_STAGE(PG8_SA(1, 1), a1 + hstepA, voffA);
;             PG8_WAIT_V(8); PG8_WAIT_L(0); PG8_BAR; PG8_MMA(0, 0, At, B0); PG8_MMA(0, 1, At, B1); PG8_BAR; PG8_SCHED;
;             PG8_LDA(At, 0, 1); PG8_STAGE(PG8_SB(0, 0), b2, voffB); PG8_STAGE(PG8_SB(0, 1), b2 + hstepB, voffB); PG8_STAGE(PG8_SA(0, 0), a2, voffA);
;             PG8_WAIT_V(8); PG8_WAIT_L(0); PG8_BAR; PG8_MMA(1, 0, At, B0); PG8_MMA(1, 1, At, B1); PG8_BAR; PG8_SCHED;
	s_setprio 1
	s_waitcnt lgkmcnt(0)
	v_mfma_f32_16x16x32_bf16 v[126:129], v[142:145], v[182:185], v[126:129]
	v_mfma_f32_16x16x32_bf16 v[122:125], v[154:157], v[182:185], v[122:125]
	v_mfma_f32_16x16x32_bf16 v[110:113], v[142:145], v[202:205], v[110:113]
	v_mfma_f32_16x16x32_bf16 v[106:109], v[154:157], v[202:205], v[106:109]
	v_mfma_f32_16x16x32_bf16 v[92:95], v[142:145], v[210:213], v[92:95]
	v_mfma_f32_16x16x32_bf16 v[88:91], v[154:157], v[210:213], v[88:91]
	v_mfma_f32_16x16x32_bf16 v[76:79], v[142:145], v[218:221], v[76:79]
	v_mfma_f32_16x16x32_bf16 v[72:75], v[154:157], v[218:221], v[72:75]
	v_mfma_f32_16x16x32_bf16 v[126:129], v[150:153], v[186:189], v[126:129]
	v_mfma_f32_16x16x32_bf16 v[122:125], v[162:165], v[186:189], v[122:125]
	v_mfma_f32_16x16x32_bf16 v[110:113], v[150:153], v[206:209], v[110:113]
	v_mfma_f32_16x16x32_bf16 v[106:109], v[162:165], v[206:209], v[106:109]
	v_mfma_f32_16x16x32_bf16 v[92:95], v[150:153], v[214:217], v[92:95]
	v_mfma_f32_16x16x32_bf16 v[88:91], v[162:165], v[214:217], v[88:91]
	v_mfma_f32_16x16x32_bf16 v[76:79], v[150:153], v[222:225], v[76:79]
	v_mfma_f32_16x16x32_bf16 v[72:75], v[162:165], v[222:225], v[72:75]
	s_setprio 0
	s_setprio 1
	v_mfma_f32_16x16x32_bf16 v[118:121], v[166:169], v[182:185], v[118:121]
	v_mfma_f32_16x16x32_bf16 v[114:117], v[174:177], v[182:185], v[114:117]
	v_mfma_f32_16x16x32_bf16 v[102:105], v[166:169], v[202:205], v[102:105]
	v_mfma_f32_16x16x32_bf16 v[98:101], v[174:177], v[202:205], v[98:101]
	v_mfma_f32_16x16x32_bf16 v[84:87], v[166:169], v[210:213], v[84:87]
	v_mfma_f32_16x16x32_bf16 v[80:83], v[174:177], v[210:213], v[80:83]
	v_mfma_f32_16x16x32_bf16 v[68:71], v[166:169], v[218:221], v[68:71]
	v_mfma_f32_16x16x32_bf16 v[64:67], v[174:177], v[218:221], v[64:67]
	v_mfma_f32_16x16x32_bf16 v[118:121], v[170:173], v[186:189], v[118:121]
	v_mfma_f32_16x16x32_bf16 v[114:117], v[178:181], v[186:189], v[114:117]
	v_mfma_f32_16x16x32_bf16 v[102:105], v[170:173], v[206:209], v[102:105]
	v_mfma_f32_16x16x32_bf16 v[98:101], v[178:181], v[206:209], v[98:101]
	v_mfma_f32_16x16x32_bf16 v[84:87], v[170:173], v[214:217], v[84:87]
	v_mfma_f32_16x16x32_bf16 v[80:83], v[178:181], v[214:217], v[80:83]
	v_mfma_f32_16x16x32_bf16 v[68:71], v[170:173], v[222:225], v[68:71]
	v_mfma_f32_16x16x32_bf16 v[64:67], v[178:181], v[222:225], v[64:67]
	s_setprio 0
	s_barrier
	s_add_i32 s46, s46, s30
	v_lshl_add_u64 v[146:147], s[22:23], 0, v[132:133]
	s_mov_b32 m0, s46
	ds_read_b128 v[182:185], v161 offset:16384
	ds_read_b128 v[186:189], v161 offset:17408
	ds_read_b128 v[202:205], v161 offset:18432
	ds_read_b128 v[206:209], v161 offset:19456
	ds_read_b128 v[210:213], v161 offset:20480
	ds_read_b128 v[214:217], v161 offset:21504
	ds_read_b128 v[218:221], v161 offset:22528
	ds_read_b128 v[222:225], v161 offset:23552
	global_load_lds_dwordx4 v[146:147], off
	s_add_i32 m0, s46, 0x2000
	s_add_u32 s72, s22, 0x20000
	v_lshl_add_u64 v[148:149], s[22:23], 0, v[136:137]
	s_addc_u32 s73, s23, 0
	s_add_i32 s46, s74, s30
	global_load_lds_dwordx4 v[148:149], off
	v_lshl_add_u64 v[226:227], s[72:73], 0, v[132:133]
	s_mov_b32 m0, s46
	v_lshl_add_u64 v[228:229], s[28:29], 0, v[134:135]
	global_load_lds_dwordx4 v[226:227], off
	v_lshl_add_u64 v[226:227], s[72:73], 0, v[136:137]
	s_add_i32 m0, s46, 0x2000
	s_nop 0
	global_load_lds_dwordx4 v[226:227], off
	v_lshl_add_u64 v[226:227], s[28:29], 0, v[130:131]
	s_mov_b32 m0, s31
	s_nop 0
	global_load_lds_dwordx4 v[226:227], off
	s_mov_b32 m0, s42
	s_nop 0
	global_load_lds_dwordx4 v[228:229], off
	s_waitcnt vmcnt(8)
	s_waitcnt lgkmcnt(0)
	s_barrier
	s_setprio 1
	s_waitcnt lgkmcnt(0)
	v_mfma_f32_16x16x32_bf16 v[60:63], v[142:145], v[182:185], v[60:63]
	v_mfma_f32_16x16x32_bf16 v[56:59], v[154:157], v[182:185], v[56:59]
	v_mfma_f32_16x16x32_bf16 v[44:47], v[142:145], v[202:205], v[44:47]
	v_mfma_f32_16x16x32_bf16 v[40:43], v[154:157], v[202:205], v[40:43]
	v_mfma_f32_16x16x32_bf16 v[28:31], v[142:145], v[210:213], v[28:31]
	v_mfma_f32_16x16x32_bf16 v[24:27], v[154:157], v[210:213], v[24:27]
	v_mfma_f32_16x16x32_bf16 v[12:15], v[142:145], v[218:221], v[12:15]
	v_mfma_f32_16x16x32_bf16 v[8:11], v[154:157], v[218:221], v[8:11]
	v_mfma_f32_16x16x32_bf16 v[60:63], v[150:153], v[186:189], v[60:63]
	v_mfma_f32_16x16x32_bf16 v[56:59], v[162:165], v[186:189], v[56:59]
	v_mfma_f32_16x16x32_bf16 v[44:47], v[150:153], v[206:209], v[44:47]
	v_mfma_f32_16x16x32_bf16 v[40:43], v[162:165], v[206:209], v[40:43]
	v_mfma_f32_16x16x32_bf16 v[28:31], v[150:153], v[214:217], v[28:31]
	v_mfma_f32_16x16x32_bf16 v[24:27], v[162:165], v[214:217], v[24:27]
	v_mfma_f32_16x16x32_bf16 v[12:15], v[150:153], v[222:225], v[12:15]
	v_mfma_f32_16x16x32_bf16 v[8:11], v[162:165], v[222:225], v[8:11]
	s_setprio 0
	s_setprio 1
	v_mfma_f32_16x16x32_bf16 v[52:55], v[166:169], v[182:185], v[52:55]
	v_mfma_f32_16x16x32_bf16 v[48:51], v[174:177], v[182:185], v[48:51]
	v_mfma_f32_16x16x32_bf16 v[36:39], v[166:169], v[202:205], v[36:39]
	v_mfma_f32_16x16x32_bf16 v[32:35], v[174:177], v[202:205], v[32:35]
	v_mfma_f32_16x16x32_bf16 v[20:23], v[166:169], v[210:213], v[20:23]
	v_mfma_f32_16x16x32_bf16 v[16:19], v[174:177], v[210:213], v[16:19]
	v_mfma_f32_16x16x32_bf16 v[4:7], v[166:169], v[218:221], v[4:7]
	v_mfma_f32_16x16x32_bf16 v[0:3], v[174:177], v[218:221], v[0:3]
	v_mfma_f32_16x16x32_bf16 v[52:55], v[170:173], v[186:189], v[52:55]
	v_mfma_f32_16x16x32_bf16 v[48:51], v[178:181], v[186:189], v[48:51]
	v_mfma_f32_16x16x32_bf16 v[36:39], v[170:173], v[206:209], v[36:39]
	v_mfma_f32_16x16x32_bf16 v[32:35], v[178:181], v[206:209], v[32:35]
	v_mfma_f32_16x16x32_bf16 v[20:23], v[170:173], v[214:217], v[20:23]
	v_mfma_f32_16x16x32_bf16 v[16:19], v[178:181], v[214:217], v[16:19]
	v_mfma_f32_16x16x32_bf16 v[4:7], v[170:173], v[222:225], v[4:7]
	v_mfma_f32_16x16x32_bf16 v[0:3], v[178:181], v[222:225], v[0:3]
	s_setprio 0
	s_barrier
; #define PG8_STAGE(bufoff, gbase, voff) do { _Pragma("unroll") for (int _i = 0; _i < 2; ++_i) \
;         __builtin_amdgcn_global_load_lds((const unsigned*)((const char*)(gbase) + (voff)[_i]), (PG8_LAS unsigned*)(lds + (bufoff) + ldsw + _i * 8192), 16, 0, 0); } while (0)
; #define PG8_LDA(dst, b, h) do { _Pragma("unroll") for (int m = 0; m < 4; ++m) _Pragma("unroll") for (int k = 0; k < 2; ++k) dst[m][k] = *(const PG8_LAS bf16x8*)(lds + PG8_SA(b, h) + aoff + m * 2048 + k * 1024); } while (0)
; #define PG8_LDB(dst, b, h) do { _Pragma("unroll") for (int n = 0; n < 2; ++n) _Pragma("unroll") for (int k = 0; k < 2; ++k) dst[n][k] = *(const PG8_LAS bf16x8*)(lds + PG8_SB(b, h) + boff + n * 2048 + k * 1024); } while (0)
; #define PG8_MMA(ai, bj, At, Bt) do { __builtin_amdgcn_s_setprio(1); _Pragma("unroll") for (int m = 0; m < 4; ++m) _Pragma("unroll") for (int n = 0; n < 2; ++n) _Pragma("unroll") for (int k = 0; k < 2; ++k) \
;         acc[ai][bj][m][n] = __builtin_amdgcn_mfma_f32_16x16x32_bf16(Bt[n][k], At[m][k], acc[ai][bj][m][n], 0, 0, 0); __builtin_amdgcn_s_setprio(0); } while (0)
; #define PG8_WAIT_V(n) asm volatile("s_waitcnt vmcnt(" #n ")" ::: "memory")
; #define PG8_WAIT_L(n) asm volatile("s_waitcnt lgkmcnt(" #n ")" ::: "memory")
; #define PG8_BAR __builtin_amdgcn_s_barrier()
; #define PG8_SCHED __builtin_amdgcn_sched_barrier(0)
; template <class Epi, class Sched, bool ALIGN_EPI = false, bool SP2 = false>
; __device__ __forceinline__ void gemm_phase(PG8_LAS unsigned char* lds, const Gemm g, const Sched& S, const Epi& E, const int tid_in) {
;     ...
;             PG8_LDB(B0, 1, 0); PG8_LDB(B1, 1, 1); PG8_SCHED; PG8_LDA(At, 1, 0); PG8_STAGE(PG8_SA(0, 1), a2 + hstepA, voffA);
;             PG8_WAIT_V(8); PG8_WAIT_L(0); PG8_BAR; PG8_MMA(0, 0, At, B0); PG8_MMA(0, 1, At, B1); PG8_BAR; PG8_SCHED;
	s_add_i32 s46, 0, 0x18000
	v_add_u32_e32 v96, s46, v159
	s_add_i32 s72, 0, 0x1c000
	ds_read_b128 v[142:145], v96
	ds_read_b128 v[150:153], v96 offset:1024
	ds_read_b128 v[154:157], v96 offset:2048
	ds_read_b128 v[162:165], v96 offset:3072
	v_add_u32_e32 v96, s72, v159
	ds_read_b128 v[166:169], v96
	ds_read_b128 v[170:173], v96 offset:1024
	ds_read_b128 v[174:177], v96 offset:2048
	ds_read_b128 v[178:181], v96 offset:3072
	s_add_u32 s28, s28, 0x20000
	s_addc_u32 s29, s29, 0
	s_mov_b32 m0, s43
	v_lshl_add_u64 v[230:231], s[28:29], 0, v[130:131]
	ds_read_b128 v[182:185], v161 offset:32768
	ds_read_b128 v[186:189], v161 offset:33792
	ds_read_b128 v[202:205], v161 offset:34816
	ds_read_b128 v[206:209], v161 offset:35840
	ds_read_b128 v[210:213], v161 offset:36864
	ds_read_b128 v[214:217], v161 offset:37888
	ds_read_b128 v[218:221], v161 offset:38912
	ds_read_b128 v[222:225], v161 offset:39936
	global_load_lds_dwordx4 v[230:231], off
	v_lshl_add_u64 v[230:231], s[28:29], 0, v[134:135]
	s_mov_b32 m0, s44
	s_nop 0
	global_load_lds_dwordx4 v[230:231], off
	s_waitcnt vmcnt(8)
	s_waitcnt lgkmcnt(0)
	s_barrier
	s_setprio 1
	s_waitcnt lgkmcnt(0)
	v_mfma_f32_16x16x32_bf16 v[126:129], v[142:145], v[182:185], v[126:129]
	v_mfma_f32_16x16x32_bf16 v[122:125], v[154:157], v[182:185], v[122:125]
	v_mfma_f32_16x16x32_bf16 v[110:113], v[142:145], v[202:205], v[110:113]
	v_mfma_f32_16x16x32_bf16 v[106:109], v[154:157], v[202:205], v[106:109]
	v_mfma_f32_16x16x32_bf16 v[92:95], v[142:145], v[210:213], v[92:95]
	v_mfma_f32_16x16x32_bf16 v[88:91], v[154:157], v[210:213], v[88:91]
	v_mfma_f32_16x16x32_bf16 v[76:79], v[142:145], v[218:221], v[76:79]
	v_mfma_f32_16x16x32_bf16 v[72:75], v[154:157], v[218:221], v[72:75]
	v_mfma_f32_16x16x32_bf16 v[126:129], v[150:153], v[186:189], v[126:129]
	v_mfma_f32_16x16x32_bf16 v[122:125], v[162:165], v[186:189], v[122:125]
	v_mfma_f32_16x16x32_bf16 v[110:113], v[150:153], v[206:209], v[110:113]
	v_mfma_f32_16x16x32_bf16 v[106:109], v[162:165], v[206:209], v[106:109]
	v_mfma_f32_16x16x32_bf16 v[92:95], v[150:153], v[214:217], v[92:95]
	v_mfma_f32_16x16x32_bf16 v[88:91], v[162:165], v[214:217], v[88:91]
	v_mfma_f32_16x16x32_bf16 v[76:79], v[150:153], v[222:225], v[76:79]
	v_mfma_f32_16x16x32_bf16 v[72:75], v[162:165], v[222:225], v[72:75]
	s_setprio 0
	s_setprio 1
	v_mfma_f32_16x16x32_bf16 v[118:121], v[166:169], v[182:185], v[118:121]
	v_mfma_f32_16x16x32_bf16 v[114:117], v[174:177], v[182:185], v[114:117]
	v_mfma_f32_16x16x32_bf16 v[102:105], v[166:169], v[202:205], v[102:105]
	v_mfma_f32_16x16x32_bf16 v[98:101], v[174:177], v[202:205], v[98:101]
	v_mfma_f32_16x16x32_bf16 v[84:87], v[166:169], v[210:213], v[84:87]
	v_mfma_f32_16x16x32_bf16 v[80:83], v[174:177], v[210:213], v[80:83]
	v_mfma_f32_16x16x32_bf16 v[68:71], v[166:169], v[218:221], v[68:71]
	v_mfma_f32_16x16x32_bf16 v[64:67], v[174:177], v[218:221], v[64:67]
	v_mfma_f32_16x16x32_bf16 v[118:121], v[170:173], v[186:189], v[118:121]
	v_mfma_f32_16x16x32_bf16 v[114:117], v[178:181], v[186:189], v[114:117]
	v_mfma_f32_16x16x32_bf16 v[102:105], v[170:173], v[206:209], v[102:105]
	v_mfma_f32_16x16x32_bf16 v[98:101], v[178:181], v[206:209], v[98:101]
	v_mfma_f32_16x16x32_bf16 v[84:87], v[170:173], v[214:217], v[84:87]
	v_mfma_f32_16x16x32_bf16 v[80:83], v[178:181], v[214:217], v[80:83]
	v_mfma_f32_16x16x32_bf16 v[68:71], v[170:173], v[222:225], v[68:71]
	v_mfma_f32_16x16x32_bf16 v[64:67], v[178:181], v[222:225], v[64:67]
	s_setprio 0
	s_barrier
; #define PG8_STAGE(bufoff, gbase, voff) do { _Pragma("unroll") for (int _i = 0; _i < 2; ++_i) \
;         __builtin_amdgcn_global_load_lds((const unsigned*)((const char*)(gbase) + (voff)[_i]), (PG8_LAS unsigned*)(lds + (bufoff) + ldsw + _i * 8192), 16, 0, 0); } while (0)
; #define PG8_LDA(dst, b, h) do { _Pragma("unroll") for (int m = 0; m < 4; ++m) _Pragma("unroll") for (int k = 0; k < 2; ++k) dst[m][k] = *(const PG8_LAS bf16x8*)(lds + PG8_SA(b, h) + aoff + m * 2048 + k * 1024); } while (0)
; #define PG8_MMA(ai, bj, At, Bt) do { __builtin_amdgcn_s_setprio(1); _Pragma("unroll") for (int m = 0; m < 4; ++m) _Pragma("unroll") for (int n = 0; n < 2; ++n) _Pragma("unroll") for (int k = 0; k < 2; ++k) \
;         acc[ai][bj][m][n] = __builtin_amdgcn_mfma_f32_16x16x32_bf16(Bt[n][k], At[m][k], acc[ai][bj][m][n], 0, 0, 0); __builtin_amdgcn_s_setprio(0); } while (0)
; #define PG8_WAIT_V(n) asm volatile("s_waitcnt vmcnt(" #n ")" ::: "memory")
; #define PG8_WAIT_L(n) asm volatile("s_waitcnt lgkmcnt(" #n ")" ::: "memory")
; #define PG8_BAR __builtin_amdgcn_s_barrier()
; #define PG8_SCHED __builtin_amdgcn_sched_barrier(0)
; template <class Epi, class Sched, bool ALIGN_EPI = false, bool SP2 = false>
; __device__ __forceinline__ void gemm_phase(PG8_LAS unsigned char* lds, const Gemm g, const Sched& S, const Epi& E, const int tid_in) {
;     ...
;             PG8_WAIT_V(8); PG8_WAIT_L(0); PG8_BAR; PG8_MMA(0, 0, At, B0); PG8_MMA(0, 1, At, B1); PG8_BAR; PG8_SCHED;
;             PG8_LDA(At, 1, 1); PG8_STAGE(PG8_SB(1, 0), b3, voffB); PG8_STAGE(PG8_SB(1, 1), b3 + hstepB, voffB); PG8_STAGE(PG8_SA(1, 0), a3, voffA);
;             PG8_WAIT_V(8); PG8_WAIT_L(0); PG8_BAR; PG8_MMA(1, 0, At, B0); PG8_MMA(1, 1, At, B1); PG8_BAR; PG8_SCHED;
	s_add_i32 s28, s46, s30
	v_lshl_add_u64 v[146:147], v[146:147], 0, s[68:69]
	s_mov_b32 m0, s28
	ds_read_b128 v[182:185], v161 offset:49152
	ds_read_b128 v[186:189], v161 offset:50176
	ds_read_b128 v[202:205], v161 offset:51200
	ds_read_b128 v[206:209], v161 offset:52224
	ds_read_b128 v[210:213], v161 offset:53248
	ds_read_b128 v[214:217], v161 offset:54272
	ds_read_b128 v[218:221], v161 offset:55296
	ds_read_b128 v[222:225], v161 offset:56320
	global_load_lds_dwordx4 v[146:147], off
	s_add_i32 m0, s28, 0x2000
	s_add_u32 s22, s22, 0x20080
	v_lshl_add_u64 v[146:147], v[148:149], 0, s[68:69]
	s_addc_u32 s23, s23, 0
	s_add_i32 s28, s72, s30
	global_load_lds_dwordx4 v[146:147], off
	v_lshl_add_u64 v[146:147], s[22:23], 0, v[132:133]
	s_mov_b32 m0, s28
	s_nop 0
	global_load_lds_dwordx4 v[146:147], off
	v_lshl_add_u64 v[146:147], s[22:23], 0, v[136:137]
	s_add_i32 m0, s28, 0x2000
	s_nop 0
	global_load_lds_dwordx4 v[146:147], off
	v_lshl_add_u64 v[146:147], v[226:227], 0, s[68:69]
	s_mov_b32 m0, s45
	s_nop 0
	global_load_lds_dwordx4 v[146:147], off
	v_lshl_add_u64 v[146:147], v[228:229], 0, s[68:69]
	s_mov_b32 m0, s52
	s_nop 0
	global_load_lds_dwordx4 v[146:147], off
	s_waitcnt vmcnt(8)
	s_waitcnt lgkmcnt(0)
	s_barrier
	s_setprio 1
	s_waitcnt lgkmcnt(0)
	v_mfma_f32_16x16x32_bf16 v[60:63], v[142:145], v[182:185], v[60:63]
	v_mfma_f32_16x16x32_bf16 v[56:59], v[154:157], v[182:185], v[56:59]
	v_mfma_f32_16x16x32_bf16 v[44:47], v[142:145], v[202:205], v[44:47]
	v_mfma_f32_16x16x32_bf16 v[40:43], v[154:157], v[202:205], v[40:43]
	v_mfma_f32_16x16x32_bf16 v[28:31], v[142:145], v[210:213], v[28:31]
	v_mfma_f32_16x16x32_bf16 v[24:27], v[154:157], v[210:213], v[24:27]
	v_mfma_f32_16x16x32_bf16 v[12:15], v[142:145], v[218:221], v[12:15]
	v_mfma_f32_16x16x32_bf16 v[8:11], v[154:157], v[218:221], v[8:11]
	v_mfma_f32_16x16x32_bf16 v[60:63], v[150:153], v[186:189], v[60:63]
	v_mfma_f32_16x16x32_bf16 v[56:59], v[162:165], v[186:189], v[56:59]
	v_mfma_f32_16x16x32_bf16 v[44:47], v[150:153], v[206:209], v[44:47]
	v_mfma_f32_16x16x32_bf16 v[40:43], v[162:165], v[206:209], v[40:43]
	v_mfma_f32_16x16x32_bf16 v[28:31], v[150:153], v[214:217], v[28:31]
	v_mfma_f32_16x16x32_bf16 v[24:27], v[162:165], v[214:217], v[24:27]
	v_mfma_f32_16x16x32_bf16 v[12:15], v[150:153], v[222:225], v[12:15]
	v_mfma_f32_16x16x32_bf16 v[8:11], v[162:165], v[222:225], v[8:11]
	s_setprio 0
	s_setprio 1
	v_mfma_f32_16x16x32_bf16 v[52:55], v[166:169], v[182:185], v[52:55]
	v_mfma_f32_16x16x32_bf16 v[48:51], v[174:177], v[182:185], v[48:51]
	v_mfma_f32_16x16x32_bf16 v[36:39], v[166:169], v[202:205], v[36:39]
	v_mfma_f32_16x16x32_bf16 v[32:35], v[174:177], v[202:205], v[32:35]
	v_mfma_f32_16x16x32_bf16 v[20:23], v[166:169], v[210:213], v[20:23]
	v_mfma_f32_16x16x32_bf16 v[16:19], v[174:177], v[210:213], v[16:19]
	v_mfma_f32_16x16x32_bf16 v[4:7], v[166:169], v[218:221], v[4:7]
	v_mfma_f32_16x16x32_bf16 v[0:3], v[174:177], v[218:221], v[0:3]
	v_mfma_f32_16x16x32_bf16 v[52:55], v[170:173], v[186:189], v[52:55]
	v_mfma_f32_16x16x32_bf16 v[48:51], v[178:181], v[186:189], v[48:51]
	v_mfma_f32_16x16x32_bf16 v[36:39], v[170:173], v[206:209], v[36:39]
	v_mfma_f32_16x16x32_bf16 v[32:35], v[178:181], v[206:209], v[32:35]
	v_mfma_f32_16x16x32_bf16 v[20:23], v[170:173], v[214:217], v[20:23]
	v_mfma_f32_16x16x32_bf16 v[16:19], v[178:181], v[214:217], v[16:19]
	v_mfma_f32_16x16x32_bf16 v[4:7], v[170:173], v[222:225], v[4:7]
	v_mfma_f32_16x16x32_bf16 v[0:3], v[178:181], v[222:225], v[0:3]
	s_setprio 0
	s_barrier
	s_add_i32 s71, s71, 2
	s_add_u32 s20, s20, 0x100
	s_addc_u32 s21, s21, 0
	s_add_u32 s60, s60, 0x100
	s_addc_u32 s70, s70, 0
	s_cmp_gt_u32 s71, 5
	s_cbranch_scc0 .LBB0_293
	s_and_b64 vcc, exec, s[8:9]
	s_cbranch_vccz .LBB0_296
	s_barrier

; __device__ __forceinline__ f32x4 ld_bf4(const bf16_t* p) { const u32x2 w = *(const u32x2*)p; f32x4 r; r[0] = __uint_as_float(w.x << 16); r[1] = __uint_as_float(w.x & 0xffff0000u); r[2] = __uint_as_float(w.y << 16); r[3] = __uint_as_float(w.y & 0xffff0000u); return r; }
; __device__ __forceinline__ void st_bf4(bf16_t* p, const f32x4 v) { u32x2 w; w.x = cvt_pk_bf16(v[0], v[1]); w.y = cvt_pk_bf16(v[2], v[3]); *(u32x2*)p = w; }
;     __device__ __forceinline__ void operator()(const f32x4 (&acc)[2][2][4][2], const Unit& u, int wr, int wc, int fr, int fq) const {
;         const int br = u.pm / 66, pm = u.pm - br * 66, pn = u.pn & 3;
;         if (br > 0) asm volatile("s_waitcnt vmcnt(0)" ::: "memory");
; #pragma unroll
;         for (int ai = 0; ai < 2; ++ai)
; #pragma unroll
;             for (int m = 0; m < 4; ++m) { const int row = pm * 256 + ai * 128 + wr * 64 + m * 16 + fr;
; #pragma unroll
;                 for (int bj = 0; bj < 2; ++bj)
; #pragma unroll
;                     for (int n = 0; n < 2; ++n) { const int col = pn * 256 + bj * 128 + wc * 32 + 8 * fq + 4 * n; const f32x4 v = acc[ai][bj][m][n];
;                         const f32x4 g = ld_bf4(GT + (size_t)row * 3072 + br * 1024 + col);
;                         bf16_t* mp = M16 + (size_t)row * 1024 + col;
;                         if (br == 0) st_bf4(mp, g * v); else st_bf4(mp, ld_bf4(mp) + g * v); } }
.LBB0_298:
	s_mul_hi_i32 s7, s6, 0x3e0f83e1
	s_lshr_b32 s11, s7, 31
	s_ashr_i32 s7, s7, 4
	s_add_i32 s7, s7, s11
	s_mul_i32 s11, s7, 0xffffffbe
	s_add_i32 s11, s11, s6
	v_lshl_add_u32 v142, s11, 8, v158
	s_lshl_b32 s11, s55, 8
	s_lshl_b32 s20, s7, 10
	s_and_b32 s11, s11, 0x300
	s_addk_i32 s6, 0x41
	v_or_b32_e32 v96, s11, v160
	s_cmpk_gt_u32 s6, 0x82
	v_lshlrev_b32_e32 v96, 1, v96
	s_cselect_b64 s[22:23], -1, 0
	v_mul_u32_u24_e32 v170, s61, v142
	v_add_u32_e32 v170, v170, v96
	v_lshl_add_u32 v170, s20, 1, v170
	v_lshl_add_u32 v186, v142, 11, v96
	v_add_u32_e32 v171, 0x18000, v170
	v_add_u32_e32 v187, 0x8000, v186
	v_add_u32_e32 v172, 0x30000, v170
	v_add_u32_e32 v188, 0x10000, v186
	v_add_u32_e32 v173, 0x48000, v170
	v_add_u32_e32 v189, 0x18000, v186
	v_add_u32_e32 v174, 0xc0000, v170
	v_add_u32_e32 v190, 0x40000, v186
	v_add_u32_e32 v175, 0xd8000, v170
	v_add_u32_e32 v191, 0x48000, v186
	v_add_u32_e32 v176, 0xf0000, v170
	v_add_u32_e32 v192, 0x50000, v186
	v_add_u32_e32 v177, 0x108000, v170
	v_add_u32_e32 v193, 0x58000, v186
	s_mov_b32 s74, 0x600000
	s_mov_b32 s72, 0xa00000
	s_mov_b32 s73, 0xc00000
	s_cmp_eq_u32 s7, 2
	s_cbranch_scc1 .Lem_final
	global_load_dwordx4 v[198:201], v170, s[2:3]
	global_load_dwordx4 v[202:205], v170, s[2:3] offset:256
	global_load_dwordx4 v[206:209], v170, s[2:3] offset:2048
	global_load_dwordx4 v[210:213], v170, s[2:3] offset:2304
	global_load_dwordx4 v[214:217], v171, s[2:3]
	global_load_dwordx4 v[218:221], v171, s[2:3] offset:256
	global_load_dwordx4 v[222:225], v171, s[2:3] offset:2048
	global_load_dwordx4 v[226:229], v171, s[2:3] offset:2304
	global_load_dwordx4 v[230:233], v172, s[2:3]
	global_load_dwordx4 v[234:237], v172, s[2:3] offset:256
	global_load_dwordx4 v[238:241], v172, s[2:3] offset:2048
	global_load_dwordx4 v[242:245], v172, s[2:3] offset:2304
	global_load_dwordx4 v[246:249], v173, s[2:3]
	global_load_dwordx4 v[250:253], v173, s[2:3] offset:256
	global_load_dwordx4 v[182:185], v173, s[2:3] offset:2048
	global_load_dwordx4 v[150:153], v173, s[2:3] offset:2304
	s_waitcnt vmcnt(12)
	v_lshlrev_b32_e32 v142, 16, v198
	v_and_b32_e32 v143, 0xffff0000, v198
	v_lshlrev_b32_e32 v144, 16, v199
	v_and_b32_e32 v145, 0xffff0000, v199
	v_lshlrev_b32_e32 v146, 16, v206
	v_and_b32_e32 v147, 0xffff0000, v206
	v_lshlrev_b32_e32 v148, 16, v207
	v_and_b32_e32 v149, 0xffff0000, v207
	v_max_f32_e32 v146, 0x2b800000, v146
	v_max_f32_e32 v147, 0x2b800000, v147
	v_max_f32_e32 v148, 0x2b800000, v148
	v_max_f32_e32 v149, 0x2b800000, v149
	v_max_f32_e32 v142, 0x2b800000, v142
	v_max_f32_e32 v143, 0x2b800000, v143
	v_max_f32_e32 v144, 0x2b800000, v144
	v_max_f32_e32 v145, 0x2b800000, v145
	v_rcp_f32_e32 v146, v146
	v_rcp_f32_e32 v147, v147
	v_rcp_f32_e32 v148, v148
	v_rcp_f32_e32 v149, v149
	s_nop 0
	v_pk_mul_f32 v[142:143], v[142:143], v[146:147]
	v_pk_mul_f32 v[144:145], v[144:145], v[148:149]
	v_pk_mul_f32 v[126:127], v[126:127], v[142:143]
	v_pk_mul_f32 v[128:129], v[128:129], v[144:145]
	v_lshlrev_b32_e32 v142, 16, v200
	v_and_b32_e32 v143, 0xffff0000, v200
	v_lshlrev_b32_e32 v144, 16, v201
	v_and_b32_e32 v145, 0xffff0000, v201
	v_lshlrev_b32_e32 v146, 16, v208
	v_and_b32_e32 v147, 0xffff0000, v208
	v_lshlrev_b32_e32 v148, 16, v209
	v_and_b32_e32 v149, 0xffff0000, v209
	v_max_f32_e32 v146, 0x2b800000, v146
	v_max_f32_e32 v147, 0x2b800000, v147
	v_max_f32_e32 v148, 0x2b800000, v148
	v_max_f32_e32 v149, 0x2b800000, v149
	v_max_f32_e32 v142, 0x2b800000, v142
	v_max_f32_e32 v143, 0x2b800000, v143
	v_max_f32_e32 v144, 0x2b800000, v144
	v_max_f32_e32 v145, 0x2b800000, v145
	v_rcp_f32_e32 v146, v146
	v_rcp_f32_e32 v147, v147
	v_rcp_f32_e32 v148, v148
	v_rcp_f32_e32 v149, v149
	s_nop 0
	v_pk_mul_f32 v[142:143], v[142:143], v[146:147]
	v_pk_mul_f32 v[144:145], v[144:145], v[148:149]
	v_pk_mul_f32 v[122:123], v[122:123], v[142:143]
	v_pk_mul_f32 v[124:125], v[124:125], v[144:145]
	v_lshlrev_b32_e32 v142, 16, v202
	v_and_b32_e32 v143, 0xffff0000, v202
	v_lshlrev_b32_e32 v144, 16, v203
	v_and_b32_e32 v145, 0xffff0000, v203
	v_lshlrev_b32_e32 v146, 16, v210
	v_and_b32_e32 v147, 0xffff0000, v210
	v_lshlrev_b32_e32 v148, 16, v211
	v_and_b32_e32 v149, 0xffff0000, v211
	v_max_f32_e32 v146, 0x2b800000, v146
	v_max_f32_e32 v147, 0x2b800000, v147
	v_max_f32_e32 v148, 0x2b800000, v148
	v_max_f32_e32 v149, 0x2b800000, v149
	v_max_f32_e32 v142, 0x2b800000, v142
	v_max_f32_e32 v143, 0x2b800000, v143
	v_max_f32_e32 v144, 0x2b800000, v144
	v_max_f32_e32 v145, 0x2b800000, v145
	v_rcp_f32_e32 v146, v146
	v_rcp_f32_e32 v147, v147
	v_rcp_f32_e32 v148, v148
	v_rcp_f32_e32 v149, v149
	s_nop 0
	v_pk_mul_f32 v[142:143], v[142:143], v[146:147]
	v_pk_mul_f32 v[144:145], v[144:145], v[148:149]
	v_pk_mul_f32 v[118:119], v[118:119], v[142:143]
	v_pk_mul_f32 v[120:121], v[120:121], v[144:145]
	v_lshlrev_b32_e32 v142, 16, v204
	v_and_b32_e32 v143, 0xffff0000, v204
	v_lshlrev_b32_e32 v144, 16, v205
	v_and_b32_e32 v145, 0xffff0000, v205
	v_lshlrev_b32_e32 v146, 16, v212
	v_and_b32_e32 v147, 0xffff0000, v212
	v_lshlrev_b32_e32 v148, 16, v213
	v_and_b32_e32 v149, 0xffff0000, v213
	v_max_f32_e32 v146, 0x2b800000, v146
	v_max_f32_e32 v147, 0x2b800000, v147
	v_max_f32_e32 v148, 0x2b800000, v148
	v_max_f32_e32 v149, 0x2b800000, v149
	v_max_f32_e32 v142, 0x2b800000, v142
	v_max_f32_e32 v143, 0x2b800000, v143
	v_max_f32_e32 v144, 0x2b800000, v144
	v_max_f32_e32 v145, 0x2b800000, v145
	v_rcp_f32_e32 v146, v146
	v_rcp_f32_e32 v147, v147
	v_rcp_f32_e32 v148, v148
	v_rcp_f32_e32 v149, v149
	s_nop 0
	v_pk_mul_f32 v[142:143], v[142:143], v[146:147]
	v_pk_mul_f32 v[144:145], v[144:145], v[148:149]
	v_pk_mul_f32 v[114:115], v[114:115], v[142:143]
	v_pk_mul_f32 v[116:117], v[116:117], v[144:145]
	global_load_dwordx4 v[198:201], v174, s[2:3]
	global_load_dwordx4 v[202:205], v174, s[2:3] offset:256
	global_load_dwordx4 v[206:209], v174, s[2:3] offset:2048
	global_load_dwordx4 v[210:213], v174, s[2:3] offset:2304
	s_waitcnt vmcnt(12)
; __device__ __forceinline__ f32x4 ld_bf4(const bf16_t* p) { const u32x2 w = *(const u32x2*)p; f32x4 r; r[0] = __uint_as_float(w.x << 16); r[1] = __uint_as_float(w.x & 0xffff0000u); r[2] = __uint_as_float(w.y << 16); r[3] = __uint_as_float(w.y & 0xffff0000u); return r; }
; __device__ __forceinline__ void st_bf4(bf16_t* p, const f32x4 v) { u32x2 w; w.x = cvt_pk_bf16(v[0], v[1]); w.y = cvt_pk_bf16(v[2], v[3]); *(u32x2*)p = w; }
;     __device__ __forceinline__ void operator()(const f32x4 (&acc)[2][2][4][2], const Unit& u, int wr, int wc, int fr, int fq) const {
;         const int br = u.pm / 66, pm = u.pm - br * 66, pn = u.pn & 3;
;         if (br > 0) asm volatile("s_waitcnt vmcnt(0)" ::: "memory");
; #pragma unroll
;         for (int ai = 0; ai < 2; ++ai)
; #pragma unroll
;             for (int m = 0; m < 4; ++m) { const int row = pm * 256 + ai * 128 + wr * 64 + m * 16 + fr;
; #pragma unroll
;                 for (int bj = 0; bj < 2; ++bj)
; #pragma unroll
;                     for (int n = 0; n < 2; ++n) { const int col = pn * 256 + bj * 128 + wc * 32 + 8 * fq + 4 * n; const f32x4 v = acc[ai][bj][m][n];
;                         const f32x4 g = ld_bf4(GT + (size_t)row * 3072 + br * 1024 + col);
;                         bf16_t* mp = M16 + (size_t)row * 1024 + col;
;                         if (br == 0) st_bf4(mp, g * v); else st_bf4(mp, ld_bf4(mp) + g * v); } }
	v_lshlrev_b32_e32 v142, 16, v214
	v_and_b32_e32 v143, 0xffff0000, v214
	v_lshlrev_b32_e32 v144, 16, v215
	v_and_b32_e32 v145, 0xffff0000, v215
	v_lshlrev_b32_e32 v146, 16, v222
	v_and_b32_e32 v147, 0xffff0000, v222
	v_lshlrev_b32_e32 v148, 16, v223
	v_and_b32_e32 v149, 0xffff0000, v223
	v_max_f32_e32 v146, 0x2b800000, v146
	v_max_f32_e32 v147, 0x2b800000, v147
	v_max_f32_e32 v148, 0x2b800000, v148
	v_max_f32_e32 v149, 0x2b800000, v149
	v_max_f32_e32 v142, 0x2b800000, v142
	v_max_f32_e32 v143, 0x2b800000, v143
	v_max_f32_e32 v144, 0x2b800000, v144
	v_max_f32_e32 v145, 0x2b800000, v145
	v_rcp_f32_e32 v146, v146
	v_rcp_f32_e32 v147, v147
	v_rcp_f32_e32 v148, v148
	v_rcp_f32_e32 v149, v149
	s_nop 0
	v_pk_mul_f32 v[142:143], v[142:143], v[146:147]
	v_pk_mul_f32 v[144:145], v[144:145], v[148:149]
	v_pk_mul_f32 v[110:111], v[110:111], v[142:143]
	v_pk_mul_f32 v[112:113], v[112:113], v[144:145]
	v_lshlrev_b32_e32 v142, 16, v216
	v_and_b32_e32 v143, 0xffff0000, v216
	v_lshlrev_b32_e32 v144, 16, v217
	v_and_b32_e32 v145, 0xffff0000, v217
	v_lshlrev_b32_e32 v146, 16, v224
	v_and_b32_e32 v147, 0xffff0000, v224
	v_lshlrev_b32_e32 v148, 16, v225
	v_and_b32_e32 v149, 0xffff0000, v225
	v_max_f32_e32 v146, 0x2b800000, v146
	v_max_f32_e32 v147, 0x2b800000, v147
	v_max_f32_e32 v148, 0x2b800000, v148
	v_max_f32_e32 v149, 0x2b800000, v149
	v_max_f32_e32 v142, 0x2b800000, v142
	v_max_f32_e32 v143, 0x2b800000, v143
	v_max_f32_e32 v144, 0x2b800000, v144
	v_max_f32_e32 v145, 0x2b800000, v145
	v_rcp_f32_e32 v146, v146
	v_rcp_f32_e32 v147, v147
	v_rcp_f32_e32 v148, v148
	v_rcp_f32_e32 v149, v149
	s_nop 0
	v_pk_mul_f32 v[142:143], v[142:143], v[146:147]
	v_pk_mul_f32 v[144:145], v[144:145], v[148:149]
	v_pk_mul_f32 v[106:107], v[106:107], v[142:143]
	v_pk_mul_f32 v[108:109], v[108:109], v[144:145]
	v_lshlrev_b32_e32 v142, 16, v218
	v_and_b32_e32 v143, 0xffff0000, v218
	v_lshlrev_b32_e32 v144, 16, v219
	v_and_b32_e32 v145, 0xffff0000, v219
	v_lshlrev_b32_e32 v146, 16, v226
	v_and_b32_e32 v147, 0xffff0000, v226
	v_lshlrev_b32_e32 v148, 16, v227
	v_and_b32_e32 v149, 0xffff0000, v227
	v_max_f32_e32 v146, 0x2b800000, v146
	v_max_f32_e32 v147, 0x2b800000, v147
	v_max_f32_e32 v148, 0x2b800000, v148
	v_max_f32_e32 v149, 0x2b800000, v149
	v_max_f32_e32 v142, 0x2b800000, v142
	v_max_f32_e32 v143, 0x2b800000, v143
	v_max_f32_e32 v144, 0x2b800000, v144
	v_max_f32_e32 v145, 0x2b800000, v145
	v_rcp_f32_e32 v146, v146
	v_rcp_f32_e32 v147, v147
	v_rcp_f32_e32 v148, v148
	v_rcp_f32_e32 v149, v149
	s_nop 0
	v_pk_mul_f32 v[142:143], v[142:143], v[146:147]
	v_pk_mul_f32 v[144:145], v[144:145], v[148:149]
	v_pk_mul_f32 v[102:103], v[102:103], v[142:143]
	v_pk_mul_f32 v[104:105], v[104:105], v[144:145]
	v_lshlrev_b32_e32 v142, 16, v220
	v_and_b32_e32 v143, 0xffff0000, v220
	v_lshlrev_b32_e32 v144, 16, v221
	v_and_b32_e32 v145, 0xffff0000, v221
	v_lshlrev_b32_e32 v146, 16, v228
	v_and_b32_e32 v147, 0xffff0000, v228
	v_lshlrev_b32_e32 v148, 16, v229
	v_and_b32_e32 v149, 0xffff0000, v229
	v_max_f32_e32 v146, 0x2b800000, v146
	v_max_f32_e32 v147, 0x2b800000, v147
	v_max_f32_e32 v148, 0x2b800000, v148
	v_max_f32_e32 v149, 0x2b800000, v149
	v_max_f32_e32 v142, 0x2b800000, v142
	v_max_f32_e32 v143, 0x2b800000, v143
	v_max_f32_e32 v144, 0x2b800000, v144
	v_max_f32_e32 v145, 0x2b800000, v145
	v_rcp_f32_e32 v146, v146
	v_rcp_f32_e32 v147, v147
	v_rcp_f32_e32 v148, v148
	v_rcp_f32_e32 v149, v149
	s_nop 0
	v_pk_mul_f32 v[142:143], v[142:143], v[146:147]
	v_pk_mul_f32 v[144:145], v[144:145], v[148:149]
	v_pk_mul_f32 v[98:99], v[98:99], v[142:143]
	v_pk_mul_f32 v[100:101], v[100:101], v[144:145]
	global_load_dwordx4 v[214:217], v175, s[2:3]
	global_load_dwordx4 v[218:221], v175, s[2:3] offset:256
	global_load_dwordx4 v[222:225], v175, s[2:3] offset:2048
	global_load_dwordx4 v[226:229], v175, s[2:3] offset:2304
	s_waitcnt vmcnt(12)
	v_lshlrev_b32_e32 v142, 16, v230
	v_and_b32_e32 v143, 0xffff0000, v230
	v_lshlrev_b32_e32 v144, 16, v231
	v_and_b32_e32 v145, 0xffff0000, v231
	v_lshlrev_b32_e32 v146, 16, v238
	v_and_b32_e32 v147, 0xffff0000, v238
	v_lshlrev_b32_e32 v148, 16, v239
	v_and_b32_e32 v149, 0xffff0000, v239
	v_max_f32_e32 v146, 0x2b800000, v146
	v_max_f32_e32 v147, 0x2b800000, v147
	v_max_f32_e32 v148, 0x2b800000, v148
	v_max_f32_e32 v149, 0x2b800000, v149
	v_max_f32_e32 v142, 0x2b800000, v142
	v_max_f32_e32 v143, 0x2b800000, v143
	v_max_f32_e32 v144, 0x2b800000, v144
	v_max_f32_e32 v145, 0x2b800000, v145
	v_rcp_f32_e32 v146, v146
	v_rcp_f32_e32 v147, v147
	v_rcp_f32_e32 v148, v148
	v_rcp_f32_e32 v149, v149
	s_nop 0
	v_pk_mul_f32 v[142:143], v[142:143], v[146:147]
	v_pk_mul_f32 v[144:145], v[144:145], v[148:149]
	v_pk_mul_f32 v[92:93], v[92:93], v[142:143]
	v_pk_mul_f32 v[94:95], v[94:95], v[144:145]
	v_lshlrev_b32_e32 v142, 16, v232
	v_and_b32_e32 v143, 0xffff0000, v232
	v_lshlrev_b32_e32 v144, 16, v233
	v_and_b32_e32 v145, 0xffff0000, v233
	v_lshlrev_b32_e32 v146, 16, v240
	v_and_b32_e32 v147, 0xffff0000, v240
	v_lshlrev_b32_e32 v148, 16, v241
	v_and_b32_e32 v149, 0xffff0000, v241
	v_max_f32_e32 v146, 0x2b800000, v146
	v_max_f32_e32 v147, 0x2b800000, v147
	v_max_f32_e32 v148, 0x2b800000, v148
	v_max_f32_e32 v149, 0x2b800000, v149
	v_max_f32_e32 v142, 0x2b800000, v142
	v_max_f32_e32 v143, 0x2b800000, v143
	v_max_f32_e32 v144, 0x2b800000, v144
	v_max_f32_e32 v145, 0x2b800000, v145
	v_rcp_f32_e32 v146, v146
	v_rcp_f32_e32 v147, v147
	v_rcp_f32_e32 v148, v148
	v_rcp_f32_e32 v149, v149
	s_nop 0
	v_pk_mul_f32 v[142:143], v[142:143], v[146:147]
	v_pk_mul_f32 v[144:145], v[144:145], v[148:149]
	v_pk_mul_f32 v[88:89], v[88:89], v[142:143]
	v_pk_mul_f32 v[90:91], v[90:91], v[144:145]
; __device__ __forceinline__ f32x4 ld_bf4(const bf16_t* p) { const u32x2 w = *(const u32x2*)p; f32x4 r; r[0] = __uint_as_float(w.x << 16); r[1] = __uint_as_float(w.x & 0xffff0000u); r[2] = __uint_as_float(w.y << 16); r[3] = __uint_as_float(w.y & 0xffff0000u); return r; }
; __device__ __forceinline__ void st_bf4(bf16_t* p, const f32x4 v) { u32x2 w; w.x = cvt_pk_bf16(v[0], v[1]); w.y = cvt_pk_bf16(v[2], v[3]); *(u32x2*)p = w; }
;     __device__ __forceinline__ void operator()(const f32x4 (&acc)[2][2][4][2], const Unit& u, int wr, int wc, int fr, int fq) const {
;         const int br = u.pm / 66, pm = u.pm - br * 66, pn = u.pn & 3;
;         if (br > 0) asm volatile("s_waitcnt vmcnt(0)" ::: "memory");
; #pragma unroll
;         for (int ai = 0; ai < 2; ++ai)
; #pragma unroll
;             for (int m = 0; m < 4; ++m) { const int row = pm * 256 + ai * 128 + wr * 64 + m * 16 + fr;
; #pragma unroll
;                 for (int bj = 0; bj < 2; ++bj)
; #pragma unroll
;                     for (int n = 0; n < 2; ++n) { const int col = pn * 256 + bj * 128 + wc * 32 + 8 * fq + 4 * n; const f32x4 v = acc[ai][bj][m][n];
;                         const f32x4 g = ld_bf4(GT + (size_t)row * 3072 + br * 1024 + col);
;                         bf16_t* mp = M16 + (size_t)row * 1024 + col;
;                         if (br == 0) st_bf4(mp, g * v); else st_bf4(mp, ld_bf4(mp) + g * v); } }
	v_lshlrev_b32_e32 v142, 16, v234
	v_and_b32_e32 v143, 0xffff0000, v234
	v_lshlrev_b32_e32 v144, 16, v235
	v_and_b32_e32 v145, 0xffff0000, v235
	v_lshlrev_b32_e32 v146, 16, v242
	v_and_b32_e32 v147, 0xffff0000, v242
	v_lshlrev_b32_e32 v148, 16, v243
	v_and_b32_e32 v149, 0xffff0000, v243
	v_max_f32_e32 v146, 0x2b800000, v146
	v_max_f32_e32 v147, 0x2b800000, v147
	v_max_f32_e32 v148, 0x2b800000, v148
	v_max_f32_e32 v149, 0x2b800000, v149
	v_max_f32_e32 v142, 0x2b800000, v142
	v_max_f32_e32 v143, 0x2b800000, v143
	v_max_f32_e32 v144, 0x2b800000, v144
	v_max_f32_e32 v145, 0x2b800000, v145
	v_rcp_f32_e32 v146, v146
	v_rcp_f32_e32 v147, v147
	v_rcp_f32_e32 v148, v148
	v_rcp_f32_e32 v149, v149
	s_nop 0
	v_pk_mul_f32 v[142:143], v[142:143], v[146:147]
	v_pk_mul_f32 v[144:145], v[144:145], v[148:149]
	v_pk_mul_f32 v[84:85], v[84:85], v[142:143]
	v_pk_mul_f32 v[86:87], v[86:87], v[144:145]
	v_lshlrev_b32_e32 v142, 16, v236
	v_and_b32_e32 v143, 0xffff0000, v236
	v_lshlrev_b32_e32 v144, 16, v237
	v_and_b32_e32 v145, 0xffff0000, v237
	v_lshlrev_b32_e32 v146, 16, v244
	v_and_b32_e32 v147, 0xffff0000, v244
	v_lshlrev_b32_e32 v148, 16, v245
	v_and_b32_e32 v149, 0xffff0000, v245
	v_max_f32_e32 v146, 0x2b800000, v146
	v_max_f32_e32 v147, 0x2b800000, v147
	v_max_f32_e32 v148, 0x2b800000, v148
	v_max_f32_e32 v149, 0x2b800000, v149
	v_max_f32_e32 v142, 0x2b800000, v142
	v_max_f32_e32 v143, 0x2b800000, v143
	v_max_f32_e32 v144, 0x2b800000, v144
	v_max_f32_e32 v145, 0x2b800000, v145
	v_rcp_f32_e32 v146, v146
	v_rcp_f32_e32 v147, v147
	v_rcp_f32_e32 v148, v148
	v_rcp_f32_e32 v149, v149
	s_nop 0
	v_pk_mul_f32 v[142:143], v[142:143], v[146:147]
	v_pk_mul_f32 v[144:145], v[144:145], v[148:149]
	v_pk_mul_f32 v[80:81], v[80:81], v[142:143]
	v_pk_mul_f32 v[82:83], v[82:83], v[144:145]
	global_load_dwordx4 v[230:233], v176, s[2:3]
	global_load_dwordx4 v[234:237], v176, s[2:3] offset:256
	global_load_dwordx4 v[238:241], v176, s[2:3] offset:2048
	global_load_dwordx4 v[242:245], v176, s[2:3] offset:2304
	s_waitcnt vmcnt(12)
	v_lshlrev_b32_e32 v142, 16, v246
	v_and_b32_e32 v143, 0xffff0000, v246
	v_lshlrev_b32_e32 v144, 16, v247
	v_and_b32_e32 v145, 0xffff0000, v247
	v_lshlrev_b32_e32 v146, 16, v182
	v_and_b32_e32 v147, 0xffff0000, v182
	v_lshlrev_b32_e32 v148, 16, v183
	v_and_b32_e32 v149, 0xffff0000, v183
	v_max_f32_e32 v146, 0x2b800000, v146
	v_max_f32_e32 v147, 0x2b800000, v147
	v_max_f32_e32 v148, 0x2b800000, v148
	v_max_f32_e32 v149, 0x2b800000, v149
	v_max_f32_e32 v142, 0x2b800000, v142
	v_max_f32_e32 v143, 0x2b800000, v143
	v_max_f32_e32 v144, 0x2b800000, v144
	v_max_f32_e32 v145, 0x2b800000, v145
	v_rcp_f32_e32 v146, v146
	v_rcp_f32_e32 v147, v147
	v_rcp_f32_e32 v148, v148
	v_rcp_f32_e32 v149, v149
	s_nop 0
	v_pk_mul_f32 v[142:143], v[142:143], v[146:147]
	v_pk_mul_f32 v[144:145], v[144:145], v[148:149]
	v_pk_mul_f32 v[76:77], v[76:77], v[142:143]
	v_pk_mul_f32 v[78:79], v[78:79], v[144:145]
	v_lshlrev_b32_e32 v142, 16, v248
	v_and_b32_e32 v143, 0xffff0000, v248
	v_lshlrev_b32_e32 v144, 16, v249
	v_and_b32_e32 v145, 0xffff0000, v249
	v_lshlrev_b32_e32 v146, 16, v184
	v_and_b32_e32 v147, 0xffff0000, v184
	v_lshlrev_b32_e32 v148, 16, v185
	v_and_b32_e32 v149, 0xffff0000, v185
	v_max_f32_e32 v146, 0x2b800000, v146
	v_max_f32_e32 v147, 0x2b800000, v147
	v_max_f32_e32 v148, 0x2b800000, v148
	v_max_f32_e32 v149, 0x2b800000, v149
	v_max_f32_e32 v142, 0x2b800000, v142
	v_max_f32_e32 v143, 0x2b800000, v143
	v_max_f32_e32 v144, 0x2b800000, v144
	v_max_f32_e32 v145, 0x2b800000, v145
	v_rcp_f32_e32 v146, v146
	v_rcp_f32_e32 v147, v147
	v_rcp_f32_e32 v148, v148
	v_rcp_f32_e32 v149, v149
	s_nop 0
	v_pk_mul_f32 v[142:143], v[142:143], v[146:147]
	v_pk_mul_f32 v[144:145], v[144:145], v[148:149]
	v_pk_mul_f32 v[72:73], v[72:73], v[142:143]
	v_pk_mul_f32 v[74:75], v[74:75], v[144:145]
	v_lshlrev_b32_e32 v142, 16, v250
	v_and_b32_e32 v143, 0xffff0000, v250
	v_lshlrev_b32_e32 v144, 16, v251
	v_and_b32_e32 v145, 0xffff0000, v251
	v_lshlrev_b32_e32 v146, 16, v150
	v_and_b32_e32 v147, 0xffff0000, v150
	v_lshlrev_b32_e32 v148, 16, v151
	v_and_b32_e32 v149, 0xffff0000, v151
	v_max_f32_e32 v146, 0x2b800000, v146
	v_max_f32_e32 v147, 0x2b800000, v147
	v_max_f32_e32 v148, 0x2b800000, v148
	v_max_f32_e32 v149, 0x2b800000, v149
	v_max_f32_e32 v142, 0x2b800000, v142
	v_max_f32_e32 v143, 0x2b800000, v143
	v_max_f32_e32 v144, 0x2b800000, v144
	v_max_f32_e32 v145, 0x2b800000, v145
	v_rcp_f32_e32 v146, v146
	v_rcp_f32_e32 v147, v147
	v_rcp_f32_e32 v148, v148
	v_rcp_f32_e32 v149, v149
	s_nop 0
	v_pk_mul_f32 v[142:143], v[142:143], v[146:147]
	v_pk_mul_f32 v[144:145], v[144:145], v[148:149]
	v_pk_mul_f32 v[68:69], v[68:69], v[142:143]
	v_pk_mul_f32 v[70:71], v[70:71], v[144:145]
	v_lshlrev_b32_e32 v142, 16, v252
	v_and_b32_e32 v143, 0xffff0000, v252
	v_lshlrev_b32_e32 v144, 16, v253
	v_and_b32_e32 v145, 0xffff0000, v253
	v_lshlrev_b32_e32 v146, 16, v152
	v_and_b32_e32 v147, 0xffff0000, v152
	v_lshlrev_b32_e32 v148, 16, v153
	v_and_b32_e32 v149, 0xffff0000, v153
	v_max_f32_e32 v146, 0x2b800000, v146
	v_max_f32_e32 v147, 0x2b800000, v147
	v_max_f32_e32 v148, 0x2b800000, v148
	v_max_f32_e32 v149, 0x2b800000, v149
	v_max_f32_e32 v142, 0x2b800000, v142
	v_max_f32_e32 v143, 0x2b800000, v143
	v_max_f32_e32 v144, 0x2b800000, v144
	v_max_f32_e32 v145, 0x2b800000, v145
	v_rcp_f32_e32 v146, v146
	v_rcp_f32_e32 v147, v147
	v_rcp_f32_e32 v148, v148
	v_rcp_f32_e32 v149, v149
	s_nop 0
	v_pk_mul_f32 v[142:143], v[142:143], v[146:147]
	v_pk_mul_f32 v[144:145], v[144:145], v[148:149]
	v_pk_mul_f32 v[64:65], v[64:65], v[142:143]
	v_pk_mul_f32 v[66:67], v[66:67], v[144:145]
	global_load_dwordx4 v[246:249], v177, s[2:3]
	global_load_dwordx4 v[250:253], v177, s[2:3] offset:256
	global_load_dwordx4 v[182:185], v177, s[2:3] offset:2048
	global_load_dwordx4 v[150:153], v177, s[2:3] offset:2304
	s_waitcnt vmcnt(12)
; __device__ __forceinline__ f32x4 ld_bf4(const bf16_t* p) { const u32x2 w = *(const u32x2*)p; f32x4 r; r[0] = __uint_as_float(w.x << 16); r[1] = __uint_as_float(w.x & 0xffff0000u); r[2] = __uint_as_float(w.y << 16); r[3] = __uint_as_float(w.y & 0xffff0000u); return r; }
; __device__ __forceinline__ void st_bf4(bf16_t* p, const f32x4 v) { u32x2 w; w.x = cvt_pk_bf16(v[0], v[1]); w.y = cvt_pk_bf16(v[2], v[3]); *(u32x2*)p = w; }
;     __device__ __forceinline__ void operator()(const f32x4 (&acc)[2][2][4][2], const Unit& u, int wr, int wc, int fr, int fq) const {
;         const int br = u.pm / 66, pm = u.pm - br * 66, pn = u.pn & 3;
;         if (br > 0) asm volatile("s_waitcnt vmcnt(0)" ::: "memory");
; #pragma unroll
;         for (int ai = 0; ai < 2; ++ai)
; #pragma unroll
;             for (int m = 0; m < 4; ++m) { const int row = pm * 256 + ai * 128 + wr * 64 + m * 16 + fr;
; #pragma unroll
;                 for (int bj = 0; bj < 2; ++bj)
; #pragma unroll
;                     for (int n = 0; n < 2; ++n) { const int col = pn * 256 + bj * 128 + wc * 32 + 8 * fq + 4 * n; const f32x4 v = acc[ai][bj][m][n];
;                         const f32x4 g = ld_bf4(GT + (size_t)row * 3072 + br * 1024 + col);
;                         bf16_t* mp = M16 + (size_t)row * 1024 + col;
;                         if (br == 0) st_bf4(mp, g * v); else st_bf4(mp, ld_bf4(mp) + g * v); } }
	v_lshlrev_b32_e32 v142, 16, v198
	v_and_b32_e32 v143, 0xffff0000, v198
	v_lshlrev_b32_e32 v144, 16, v199
	v_and_b32_e32 v145, 0xffff0000, v199
	v_lshlrev_b32_e32 v146, 16, v206
	v_and_b32_e32 v147, 0xffff0000, v206
	v_lshlrev_b32_e32 v148, 16, v207
	v_and_b32_e32 v149, 0xffff0000, v207
	v_max_f32_e32 v146, 0x2b800000, v146
	v_max_f32_e32 v147, 0x2b800000, v147
	v_max_f32_e32 v148, 0x2b800000, v148
	v_max_f32_e32 v149, 0x2b800000, v149
	v_max_f32_e32 v142, 0x2b800000, v142
	v_max_f32_e32 v143, 0x2b800000, v143
	v_max_f32_e32 v144, 0x2b800000, v144
	v_max_f32_e32 v145, 0x2b800000, v145
	v_rcp_f32_e32 v146, v146
	v_rcp_f32_e32 v147, v147
	v_rcp_f32_e32 v148, v148
	v_rcp_f32_e32 v149, v149
	s_nop 0
	v_pk_mul_f32 v[142:143], v[142:143], v[146:147]
	v_pk_mul_f32 v[144:145], v[144:145], v[148:149]
	v_pk_mul_f32 v[60:61], v[60:61], v[142:143]
	v_pk_mul_f32 v[62:63], v[62:63], v[144:145]
	v_lshlrev_b32_e32 v142, 16, v200
	v_and_b32_e32 v143, 0xffff0000, v200
	v_lshlrev_b32_e32 v144, 16, v201
	v_and_b32_e32 v145, 0xffff0000, v201
	v_lshlrev_b32_e32 v146, 16, v208
	v_and_b32_e32 v147, 0xffff0000, v208
	v_lshlrev_b32_e32 v148, 16, v209
	v_and_b32_e32 v149, 0xffff0000, v209
	v_max_f32_e32 v146, 0x2b800000, v146
	v_max_f32_e32 v147, 0x2b800000, v147
	v_max_f32_e32 v148, 0x2b800000, v148
	v_max_f32_e32 v149, 0x2b800000, v149
	v_max_f32_e32 v142, 0x2b800000, v142
	v_max_f32_e32 v143, 0x2b800000, v143
	v_max_f32_e32 v144, 0x2b800000, v144
	v_max_f32_e32 v145, 0x2b800000, v145
	v_rcp_f32_e32 v146, v146
	v_rcp_f32_e32 v147, v147
	v_rcp_f32_e32 v148, v148
	v_rcp_f32_e32 v149, v149
	s_nop 0
	v_pk_mul_f32 v[142:143], v[142:143], v[146:147]
	v_pk_mul_f32 v[144:145], v[144:145], v[148:149]
	v_pk_mul_f32 v[56:57], v[56:57], v[142:143]
	v_pk_mul_f32 v[58:59], v[58:59], v[144:145]
	v_lshlrev_b32_e32 v142, 16, v202
	v_and_b32_e32 v143, 0xffff0000, v202
	v_lshlrev_b32_e32 v144, 16, v203
	v_and_b32_e32 v145, 0xffff0000, v203
	v_lshlrev_b32_e32 v146, 16, v210
	v_and_b32_e32 v147, 0xffff0000, v210
	v_lshlrev_b32_e32 v148, 16, v211
	v_and_b32_e32 v149, 0xffff0000, v211
	v_max_f32_e32 v146, 0x2b800000, v146
	v_max_f32_e32 v147, 0x2b800000, v147
	v_max_f32_e32 v148, 0x2b800000, v148
	v_max_f32_e32 v149, 0x2b800000, v149
	v_max_f32_e32 v142, 0x2b800000, v142
	v_max_f32_e32 v143, 0x2b800000, v143
	v_max_f32_e32 v144, 0x2b800000, v144
	v_max_f32_e32 v145, 0x2b800000, v145
	v_rcp_f32_e32 v146, v146
	v_rcp_f32_e32 v147, v147
	v_rcp_f32_e32 v148, v148
	v_rcp_f32_e32 v149, v149
	s_nop 0
	v_pk_mul_f32 v[142:143], v[142:143], v[146:147]
	v_pk_mul_f32 v[144:145], v[144:145], v[148:149]
	v_pk_mul_f32 v[52:53], v[52:53], v[142:143]
	v_pk_mul_f32 v[54:55], v[54:55], v[144:145]
	v_lshlrev_b32_e32 v142, 16, v204
	v_and_b32_e32 v143, 0xffff0000, v204
	v_lshlrev_b32_e32 v144, 16, v205
	v_and_b32_e32 v145, 0xffff0000, v205
	v_lshlrev_b32_e32 v146, 16, v212
	v_and_b32_e32 v147, 0xffff0000, v212
	v_lshlrev_b32_e32 v148, 16, v213
	v_and_b32_e32 v149, 0xffff0000, v213
	v_max_f32_e32 v146, 0x2b800000, v146
	v_max_f32_e32 v147, 0x2b800000, v147
	v_max_f32_e32 v148, 0x2b800000, v148
	v_max_f32_e32 v149, 0x2b800000, v149
	v_max_f32_e32 v142, 0x2b800000, v142
	v_max_f32_e32 v143, 0x2b800000, v143
	v_max_f32_e32 v144, 0x2b800000, v144
	v_max_f32_e32 v145, 0x2b800000, v145
	v_rcp_f32_e32 v146, v146
	v_rcp_f32_e32 v147, v147
	v_rcp_f32_e32 v148, v148
	v_rcp_f32_e32 v149, v149
	s_nop 0
	v_pk_mul_f32 v[142:143], v[142:143], v[146:147]
	v_pk_mul_f32 v[144:145], v[144:145], v[148:149]
	v_pk_mul_f32 v[48:49], v[48:49], v[142:143]
	v_pk_mul_f32 v[50:51], v[50:51], v[144:145]
	s_waitcnt vmcnt(8)
	v_lshlrev_b32_e32 v142, 16, v214
	v_and_b32_e32 v143, 0xffff0000, v214
	v_lshlrev_b32_e32 v144, 16, v215
	v_and_b32_e32 v145, 0xffff0000, v215
	v_lshlrev_b32_e32 v146, 16, v222
	v_and_b32_e32 v147, 0xffff0000, v222
	v_lshlrev_b32_e32 v148, 16, v223
	v_and_b32_e32 v149, 0xffff0000, v223
	v_max_f32_e32 v146, 0x2b800000, v146
	v_max_f32_e32 v147, 0x2b800000, v147
	v_max_f32_e32 v148, 0x2b800000, v148
	v_max_f32_e32 v149, 0x2b800000, v149
	v_max_f32_e32 v142, 0x2b800000, v142
	v_max_f32_e32 v143, 0x2b800000, v143
	v_max_f32_e32 v144, 0x2b800000, v144
	v_max_f32_e32 v145, 0x2b800000, v145
	v_rcp_f32_e32 v146, v146
	v_rcp_f32_e32 v147, v147
	v_rcp_f32_e32 v148, v148
	v_rcp_f32_e32 v149, v149
	s_nop 0
	v_pk_mul_f32 v[142:143], v[142:143], v[146:147]
	v_pk_mul_f32 v[144:145], v[144:145], v[148:149]
	v_pk_mul_f32 v[44:45], v[44:45], v[142:143]
	v_pk_mul_f32 v[46:47], v[46:47], v[144:145]
	v_lshlrev_b32_e32 v142, 16, v216
	v_and_b32_e32 v143, 0xffff0000, v216
	v_lshlrev_b32_e32 v144, 16, v217
	v_and_b32_e32 v145, 0xffff0000, v217
	v_lshlrev_b32_e32 v146, 16, v224
	v_and_b32_e32 v147, 0xffff0000, v224
	v_lshlrev_b32_e32 v148, 16, v225
	v_and_b32_e32 v149, 0xffff0000, v225
	v_max_f32_e32 v146, 0x2b800000, v146
	v_max_f32_e32 v147, 0x2b800000, v147
	v_max_f32_e32 v148, 0x2b800000, v148
	v_max_f32_e32 v149, 0x2b800000, v149
	v_max_f32_e32 v142, 0x2b800000, v142
	v_max_f32_e32 v143, 0x2b800000, v143
	v_max_f32_e32 v144, 0x2b800000, v144
	v_max_f32_e32 v145, 0x2b800000, v145
	v_rcp_f32_e32 v146, v146
	v_rcp_f32_e32 v147, v147
	v_rcp_f32_e32 v148, v148
	v_rcp_f32_e32 v149, v149
	s_nop 0
	v_pk_mul_f32 v[142:143], v[142:143], v[146:147]
	v_pk_mul_f32 v[144:145], v[144:145], v[148:149]
	v_pk_mul_f32 v[40:41], v[40:41], v[142:143]
	v_pk_mul_f32 v[42:43], v[42:43], v[144:145]
	v_lshlrev_b32_e32 v142, 16, v218
	v_and_b32_e32 v143, 0xffff0000, v218
	v_lshlrev_b32_e32 v144, 16, v219
	v_and_b32_e32 v145, 0xffff0000, v219
	v_lshlrev_b32_e32 v146, 16, v226
	v_and_b32_e32 v147, 0xffff0000, v226
	v_lshlrev_b32_e32 v148, 16, v227
; __device__ __forceinline__ f32x4 ld_bf4(const bf16_t* p) { const u32x2 w = *(const u32x2*)p; f32x4 r; r[0] = __uint_as_float(w.x << 16); r[1] = __uint_as_float(w.x & 0xffff0000u); r[2] = __uint_as_float(w.y << 16); r[3] = __uint_as_float(w.y & 0xffff0000u); return r; }
; __device__ __forceinline__ void st_bf4(bf16_t* p, const f32x4 v) { u32x2 w; w.x = cvt_pk_bf16(v[0], v[1]); w.y = cvt_pk_bf16(v[2], v[3]); *(u32x2*)p = w; }
;     __device__ __forceinline__ void operator()(const f32x4 (&acc)[2][2][4][2], const Unit& u, int wr, int wc, int fr, int fq) const {
;         const int br = u.pm / 66, pm = u.pm - br * 66, pn = u.pn & 3;
;         if (br > 0) asm volatile("s_waitcnt vmcnt(0)" ::: "memory");
; #pragma unroll
;         for (int ai = 0; ai < 2; ++ai)
; #pragma unroll
;             for (int m = 0; m < 4; ++m) { const int row = pm * 256 + ai * 128 + wr * 64 + m * 16 + fr;
; #pragma unroll
;                 for (int bj = 0; bj < 2; ++bj)
; #pragma unroll
;                     for (int n = 0; n < 2; ++n) { const int col = pn * 256 + bj * 128 + wc * 32 + 8 * fq + 4 * n; const f32x4 v = acc[ai][bj][m][n];
;                         const f32x4 g = ld_bf4(GT + (size_t)row * 3072 + br * 1024 + col);
;                         bf16_t* mp = M16 + (size_t)row * 1024 + col;
;                         if (br == 0) st_bf4(mp, g * v); else st_bf4(mp, ld_bf4(mp) + g * v); } }
	v_and_b32_e32 v149, 0xffff0000, v227
	v_max_f32_e32 v146, 0x2b800000, v146
	v_max_f32_e32 v147, 0x2b800000, v147
	v_max_f32_e32 v148, 0x2b800000, v148
	v_max_f32_e32 v149, 0x2b800000, v149
	v_max_f32_e32 v142, 0x2b800000, v142
	v_max_f32_e32 v143, 0x2b800000, v143
	v_max_f32_e32 v144, 0x2b800000, v144
	v_max_f32_e32 v145, 0x2b800000, v145
	v_rcp_f32_e32 v146, v146
	v_rcp_f32_e32 v147, v147
	v_rcp_f32_e32 v148, v148
	v_rcp_f32_e32 v149, v149
	s_nop 0
	v_pk_mul_f32 v[142:143], v[142:143], v[146:147]
	v_pk_mul_f32 v[144:145], v[144:145], v[148:149]
	v_pk_mul_f32 v[36:37], v[36:37], v[142:143]
	v_pk_mul_f32 v[38:39], v[38:39], v[144:145]
	v_lshlrev_b32_e32 v142, 16, v220
	v_and_b32_e32 v143, 0xffff0000, v220
	v_lshlrev_b32_e32 v144, 16, v221
	v_and_b32_e32 v145, 0xffff0000, v221
	v_lshlrev_b32_e32 v146, 16, v228
	v_and_b32_e32 v147, 0xffff0000, v228
	v_lshlrev_b32_e32 v148, 16, v229
	v_and_b32_e32 v149, 0xffff0000, v229
	v_max_f32_e32 v146, 0x2b800000, v146
	v_max_f32_e32 v147, 0x2b800000, v147
	v_max_f32_e32 v148, 0x2b800000, v148
	v_max_f32_e32 v149, 0x2b800000, v149
	v_max_f32_e32 v142, 0x2b800000, v142
	v_max_f32_e32 v143, 0x2b800000, v143
	v_max_f32_e32 v144, 0x2b800000, v144
	v_max_f32_e32 v145, 0x2b800000, v145
	v_rcp_f32_e32 v146, v146
	v_rcp_f32_e32 v147, v147
	v_rcp_f32_e32 v148, v148
	v_rcp_f32_e32 v149, v149
	s_nop 0
	v_pk_mul_f32 v[142:143], v[142:143], v[146:147]
	v_pk_mul_f32 v[144:145], v[144:145], v[148:149]
	v_pk_mul_f32 v[32:33], v[32:33], v[142:143]
	v_pk_mul_f32 v[34:35], v[34:35], v[144:145]
	s_waitcnt vmcnt(4)
	v_lshlrev_b32_e32 v142, 16, v230
	v_and_b32_e32 v143, 0xffff0000, v230
	v_lshlrev_b32_e32 v144, 16, v231
	v_and_b32_e32 v145, 0xffff0000, v231
	v_lshlrev_b32_e32 v146, 16, v238
	v_and_b32_e32 v147, 0xffff0000, v238
	v_lshlrev_b32_e32 v148, 16, v239
	v_and_b32_e32 v149, 0xffff0000, v239
	v_max_f32_e32 v146, 0x2b800000, v146
	v_max_f32_e32 v147, 0x2b800000, v147
	v_max_f32_e32 v148, 0x2b800000, v148
	v_max_f32_e32 v149, 0x2b800000, v149
	v_max_f32_e32 v142, 0x2b800000, v142
	v_max_f32_e32 v143, 0x2b800000, v143
	v_max_f32_e32 v144, 0x2b800000, v144
	v_max_f32_e32 v145, 0x2b800000, v145
	v_rcp_f32_e32 v146, v146
	v_rcp_f32_e32 v147, v147
	v_rcp_f32_e32 v148, v148
	v_rcp_f32_e32 v149, v149
	s_nop 0
	v_pk_mul_f32 v[142:143], v[142:143], v[146:147]
	v_pk_mul_f32 v[144:145], v[144:145], v[148:149]
	v_pk_mul_f32 v[28:29], v[28:29], v[142:143]
	v_pk_mul_f32 v[30:31], v[30:31], v[144:145]
	v_lshlrev_b32_e32 v142, 16, v232
	v_and_b32_e32 v143, 0xffff0000, v232
	v_lshlrev_b32_e32 v144, 16, v233
	v_and_b32_e32 v145, 0xffff0000, v233
	v_lshlrev_b32_e32 v146, 16, v240
	v_and_b32_e32 v147, 0xffff0000, v240
	v_lshlrev_b32_e32 v148, 16, v241
	v_and_b32_e32 v149, 0xffff0000, v241
	v_max_f32_e32 v146, 0x2b800000, v146
	v_max_f32_e32 v147, 0x2b800000, v147
	v_max_f32_e32 v148, 0x2b800000, v148
	v_max_f32_e32 v149, 0x2b800000, v149
	v_max_f32_e32 v142, 0x2b800000, v142
	v_max_f32_e32 v143, 0x2b800000, v143
	v_max_f32_e32 v144, 0x2b800000, v144
	v_max_f32_e32 v145, 0x2b800000, v145
	v_rcp_f32_e32 v146, v146
	v_rcp_f32_e32 v147, v147
	v_rcp_f32_e32 v148, v148
	v_rcp_f32_e32 v149, v149
	s_nop 0
	v_pk_mul_f32 v[142:143], v[142:143], v[146:147]
	v_pk_mul_f32 v[144:145], v[144:145], v[148:149]
	v_pk_mul_f32 v[24:25], v[24:25], v[142:143]
	v_pk_mul_f32 v[26:27], v[26:27], v[144:145]
	v_lshlrev_b32_e32 v142, 16, v234
	v_and_b32_e32 v143, 0xffff0000, v234
	v_lshlrev_b32_e32 v144, 16, v235
	v_and_b32_e32 v145, 0xffff0000, v235
	v_lshlrev_b32_e32 v146, 16, v242
	v_and_b32_e32 v147, 0xffff0000, v242
	v_lshlrev_b32_e32 v148, 16, v243
	v_and_b32_e32 v149, 0xffff0000, v243
	v_max_f32_e32 v146, 0x2b800000, v146
	v_max_f32_e32 v147, 0x2b800000, v147
	v_max_f32_e32 v148, 0x2b800000, v148
	v_max_f32_e32 v149, 0x2b800000, v149
	v_max_f32_e32 v142, 0x2b800000, v142
	v_max_f32_e32 v143, 0x2b800000, v143
	v_max_f32_e32 v144, 0x2b800000, v144
	v_max_f32_e32 v145, 0x2b800000, v145
	v_rcp_f32_e32 v146, v146
	v_rcp_f32_e32 v147, v147
	v_rcp_f32_e32 v148, v148
	v_rcp_f32_e32 v149, v149
	s_nop 0
	v_pk_mul_f32 v[142:143], v[142:143], v[146:147]
	v_pk_mul_f32 v[144:145], v[144:145], v[148:149]
	v_pk_mul_f32 v[20:21], v[20:21], v[142:143]
	v_pk_mul_f32 v[22:23], v[22:23], v[144:145]
	v_lshlrev_b32_e32 v142, 16, v236
	v_and_b32_e32 v143, 0xffff0000, v236
	v_lshlrev_b32_e32 v144, 16, v237
	v_and_b32_e32 v145, 0xffff0000, v237
	v_lshlrev_b32_e32 v146, 16, v244
	v_and_b32_e32 v147, 0xffff0000, v244
	v_lshlrev_b32_e32 v148, 16, v245
	v_and_b32_e32 v149, 0xffff0000, v245
	v_max_f32_e32 v146, 0x2b800000, v146
	v_max_f32_e32 v147, 0x2b800000, v147
	v_max_f32_e32 v148, 0x2b800000, v148
	v_max_f32_e32 v149, 0x2b800000, v149
	v_max_f32_e32 v142, 0x2b800000, v142
	v_max_f32_e32 v143, 0x2b800000, v143
	v_max_f32_e32 v144, 0x2b800000, v144
	v_max_f32_e32 v145, 0x2b800000, v145
	v_rcp_f32_e32 v146, v146
	v_rcp_f32_e32 v147, v147
	v_rcp_f32_e32 v148, v148
	v_rcp_f32_e32 v149, v149
	s_nop 0
	v_pk_mul_f32 v[142:143], v[142:143], v[146:147]
	v_pk_mul_f32 v[144:145], v[144:145], v[148:149]
	v_pk_mul_f32 v[16:17], v[16:17], v[142:143]
	v_pk_mul_f32 v[18:19], v[18:19], v[144:145]
	s_waitcnt vmcnt(0)
; __device__ __forceinline__ f32x4 ld_bf4(const bf16_t* p) { const u32x2 w = *(const u32x2*)p; f32x4 r; r[0] = __uint_as_float(w.x << 16); r[1] = __uint_as_float(w.x & 0xffff0000u); r[2] = __uint_as_float(w.y << 16); r[3] = __uint_as_float(w.y & 0xffff0000u); return r; }
; __device__ __forceinline__ void st_bf4(bf16_t* p, const f32x4 v) { u32x2 w; w.x = cvt_pk_bf16(v[0], v[1]); w.y = cvt_pk_bf16(v[2], v[3]); *(u32x2*)p = w; }
;     __device__ __forceinline__ void operator()(const f32x4 (&acc)[2][2][4][2], const Unit& u, int wr, int wc, int fr, int fq) const {
;         const int br = u.pm / 66, pm = u.pm - br * 66, pn = u.pn & 3;
;         if (br > 0) asm volatile("s_waitcnt vmcnt(0)" ::: "memory");
; #pragma unroll
;         for (int ai = 0; ai < 2; ++ai)
; #pragma unroll
;             for (int m = 0; m < 4; ++m) { const int row = pm * 256 + ai * 128 + wr * 64 + m * 16 + fr;
; #pragma unroll
;                 for (int bj = 0; bj < 2; ++bj)
; #pragma unroll
;                     for (int n = 0; n < 2; ++n) { const int col = pn * 256 + bj * 128 + wc * 32 + 8 * fq + 4 * n; const f32x4 v = acc[ai][bj][m][n];
;                         const f32x4 g = ld_bf4(GT + (size_t)row * 3072 + br * 1024 + col);
;                         bf16_t* mp = M16 + (size_t)row * 1024 + col;
;                         if (br == 0) st_bf4(mp, g * v); else st_bf4(mp, ld_bf4(mp) + g * v); } }
	v_lshlrev_b32_e32 v142, 16, v246
	v_and_b32_e32 v143, 0xffff0000, v246
	v_lshlrev_b32_e32 v144, 16, v247
	v_and_b32_e32 v145, 0xffff0000, v247
	v_lshlrev_b32_e32 v146, 16, v182
	v_and_b32_e32 v147, 0xffff0000, v182
	v_lshlrev_b32_e32 v148, 16, v183
	v_and_b32_e32 v149, 0xffff0000, v183
	v_max_f32_e32 v146, 0x2b800000, v146
	v_max_f32_e32 v147, 0x2b800000, v147
	v_max_f32_e32 v148, 0x2b800000, v148
	v_max_f32_e32 v149, 0x2b800000, v149
	v_max_f32_e32 v142, 0x2b800000, v142
	v_max_f32_e32 v143, 0x2b800000, v143
	v_max_f32_e32 v144, 0x2b800000, v144
	v_max_f32_e32 v145, 0x2b800000, v145
	v_rcp_f32_e32 v146, v146
	v_rcp_f32_e32 v147, v147
	v_rcp_f32_e32 v148, v148
	v_rcp_f32_e32 v149, v149
	s_nop 0
	v_pk_mul_f32 v[142:143], v[142:143], v[146:147]
	v_pk_mul_f32 v[144:145], v[144:145], v[148:149]
	v_pk_mul_f32 v[12:13], v[12:13], v[142:143]
	v_pk_mul_f32 v[14:15], v[14:15], v[144:145]
	v_lshlrev_b32_e32 v142, 16, v248
	v_and_b32_e32 v143, 0xffff0000, v248
	v_lshlrev_b32_e32 v144, 16, v249
	v_and_b32_e32 v145, 0xffff0000, v249
	v_lshlrev_b32_e32 v146, 16, v184
	v_and_b32_e32 v147, 0xffff0000, v184
	v_lshlrev_b32_e32 v148, 16, v185
	v_and_b32_e32 v149, 0xffff0000, v185
	v_max_f32_e32 v146, 0x2b800000, v146
	v_max_f32_e32 v147, 0x2b800000, v147
	v_max_f32_e32 v148, 0x2b800000, v148
	v_max_f32_e32 v149, 0x2b800000, v149
	v_max_f32_e32 v142, 0x2b800000, v142
	v_max_f32_e32 v143, 0x2b800000, v143
	v_max_f32_e32 v144, 0x2b800000, v144
	v_max_f32_e32 v145, 0x2b800000, v145
	v_rcp_f32_e32 v146, v146
	v_rcp_f32_e32 v147, v147
	v_rcp_f32_e32 v148, v148
	v_rcp_f32_e32 v149, v149
	s_nop 0
	v_pk_mul_f32 v[142:143], v[142:143], v[146:147]
	v_pk_mul_f32 v[144:145], v[144:145], v[148:149]
	v_pk_mul_f32 v[8:9], v[8:9], v[142:143]
	v_pk_mul_f32 v[10:11], v[10:11], v[144:145]
	v_lshlrev_b32_e32 v142, 16, v250
	v_and_b32_e32 v143, 0xffff0000, v250
	v_lshlrev_b32_e32 v144, 16, v251
	v_and_b32_e32 v145, 0xffff0000, v251
	v_lshlrev_b32_e32 v146, 16, v150
	v_and_b32_e32 v147, 0xffff0000, v150
	v_lshlrev_b32_e32 v148, 16, v151
	v_and_b32_e32 v149, 0xffff0000, v151
	v_max_f32_e32 v146, 0x2b800000, v146
	v_max_f32_e32 v147, 0x2b800000, v147
	v_max_f32_e32 v148, 0x2b800000, v148
	v_max_f32_e32 v149, 0x2b800000, v149
	v_max_f32_e32 v142, 0x2b800000, v142
	v_max_f32_e32 v143, 0x2b800000, v143
	v_max_f32_e32 v144, 0x2b800000, v144
	v_max_f32_e32 v145, 0x2b800000, v145
	v_rcp_f32_e32 v146, v146
	v_rcp_f32_e32 v147, v147
	v_rcp_f32_e32 v148, v148
	v_rcp_f32_e32 v149, v149
	s_nop 0
	v_pk_mul_f32 v[142:143], v[142:143], v[146:147]
	v_pk_mul_f32 v[144:145], v[144:145], v[148:149]
	v_pk_mul_f32 v[4:5], v[4:5], v[142:143]
	v_pk_mul_f32 v[6:7], v[6:7], v[144:145]
	v_lshlrev_b32_e32 v142, 16, v252
	v_and_b32_e32 v143, 0xffff0000, v252
	v_lshlrev_b32_e32 v144, 16, v253
	v_and_b32_e32 v145, 0xffff0000, v253
	v_lshlrev_b32_e32 v146, 16, v152
	v_and_b32_e32 v147, 0xffff0000, v152
	v_lshlrev_b32_e32 v148, 16, v153
	v_and_b32_e32 v149, 0xffff0000, v153
	v_max_f32_e32 v146, 0x2b800000, v146
	v_max_f32_e32 v147, 0x2b800000, v147
	v_max_f32_e32 v148, 0x2b800000, v148
	v_max_f32_e32 v149, 0x2b800000, v149
	v_max_f32_e32 v142, 0x2b800000, v142
	v_max_f32_e32 v143, 0x2b800000, v143
	v_max_f32_e32 v144, 0x2b800000, v144
	v_max_f32_e32 v145, 0x2b800000, v145
	v_rcp_f32_e32 v146, v146
	v_rcp_f32_e32 v147, v147
	v_rcp_f32_e32 v148, v148
	v_rcp_f32_e32 v149, v149
	s_nop 0
	v_pk_mul_f32 v[142:143], v[142:143], v[146:147]
	v_pk_mul_f32 v[144:145], v[144:145], v[148:149]
	v_pk_mul_f32 v[0:1], v[0:1], v[142:143]
	v_pk_mul_f32 v[2:3], v[2:3], v[144:145]
	s_branch .Lem_done
.Lem_final:
	global_load_dwordx4 v[198:201], v170, s[2:3]
	global_load_dwordx4 v[202:205], v170, s[2:3] offset:256
	global_load_dwordx4 v[206:209], v171, s[2:3]
	global_load_dwordx4 v[210:213], v171, s[2:3] offset:256
	global_load_dwordx4 v[214:217], v172, s[2:3]
	global_load_dwordx4 v[218:221], v172, s[2:3] offset:256
	global_load_dwordx4 v[222:225], v173, s[2:3]
	global_load_dwordx4 v[226:229], v173, s[2:3] offset:256
	global_load_dwordx4 v[230:233], v174, s[2:3]
	global_load_dwordx4 v[234:237], v174, s[2:3] offset:256
	global_load_dwordx4 v[238:241], v175, s[2:3]
	global_load_dwordx4 v[242:245], v175, s[2:3] offset:256
	global_load_dwordx4 v[246:249], v176, s[2:3]
	global_load_dwordx4 v[250:253], v176, s[2:3] offset:256
	global_load_dwordx4 v[182:185], v177, s[2:3]
	global_load_dwordx4 v[150:153], v177, s[2:3] offset:256
	s_waitcnt vmcnt(14)
	v_lshlrev_b32_e32 v142, 16, v198
	v_and_b32_e32 v143, 0xffff0000, v198
	v_lshlrev_b32_e32 v144, 16, v199
	v_and_b32_e32 v145, 0xffff0000, v199
	v_max_f32_e32 v142, 0x2b800000, v142
	v_max_f32_e32 v143, 0x2b800000, v143
	v_max_f32_e32 v144, 0x2b800000, v144
	v_max_f32_e32 v145, 0x2b800000, v145
	v_pk_mul_f32 v[126:127], v[126:127], v[142:143]
	v_pk_mul_f32 v[128:129], v[128:129], v[144:145]
	v_cvt_pk_bf16_f32 v198, v126, v127
	v_cvt_pk_bf16_f32 v199, v128, v129
	v_lshlrev_b32_e32 v142, 16, v200
	v_and_b32_e32 v143, 0xffff0000, v200
	v_lshlrev_b32_e32 v144, 16, v201
	v_and_b32_e32 v145, 0xffff0000, v201
	v_max_f32_e32 v142, 0x2b800000, v142
	v_max_f32_e32 v143, 0x2b800000, v143
	v_max_f32_e32 v144, 0x2b800000, v144
	v_max_f32_e32 v145, 0x2b800000, v145
	v_pk_mul_f32 v[122:123], v[122:123], v[142:143]
	v_pk_mul_f32 v[124:125], v[124:125], v[144:145]
	v_cvt_pk_bf16_f32 v200, v122, v123
	v_cvt_pk_bf16_f32 v201, v124, v125
	v_lshlrev_b32_e32 v142, 16, v202
	v_and_b32_e32 v143, 0xffff0000, v202
	v_lshlrev_b32_e32 v144, 16, v203
	v_and_b32_e32 v145, 0xffff0000, v203
	v_max_f32_e32 v142, 0x2b800000, v142
	v_max_f32_e32 v143, 0x2b800000, v143
	v_max_f32_e32 v144, 0x2b800000, v144
	v_max_f32_e32 v145, 0x2b800000, v145
	v_pk_mul_f32 v[118:119], v[118:119], v[142:143]
	v_pk_mul_f32 v[120:121], v[120:121], v[144:145]
	v_cvt_pk_bf16_f32 v202, v118, v119
	v_cvt_pk_bf16_f32 v203, v120, v121
	v_lshlrev_b32_e32 v142, 16, v204
	v_and_b32_e32 v143, 0xffff0000, v204
	v_lshlrev_b32_e32 v144, 16, v205
	v_and_b32_e32 v145, 0xffff0000, v205
	v_max_f32_e32 v142, 0x2b800000, v142
	v_max_f32_e32 v143, 0x2b800000, v143
	v_max_f32_e32 v144, 0x2b800000, v144
	v_max_f32_e32 v145, 0x2b800000, v145
	v_pk_mul_f32 v[114:115], v[114:115], v[142:143]
	v_pk_mul_f32 v[116:117], v[116:117], v[144:145]
	v_cvt_pk_bf16_f32 v204, v114, v115
	v_cvt_pk_bf16_f32 v205, v116, v117
	global_store_dwordx4 v186, v[198:201], s[88:89]
	global_store_dwordx4 v186, v[202:205], s[88:89] offset:256
	s_waitcnt vmcnt(14)
; __device__ __forceinline__ f32x4 ld_bf4(const bf16_t* p) { const u32x2 w = *(const u32x2*)p; f32x4 r; r[0] = __uint_as_float(w.x << 16); r[1] = __uint_as_float(w.x & 0xffff0000u); r[2] = __uint_as_float(w.y << 16); r[3] = __uint_as_float(w.y & 0xffff0000u); return r; }
; __device__ __forceinline__ void st_bf4(bf16_t* p, const f32x4 v) { u32x2 w; w.x = cvt_pk_bf16(v[0], v[1]); w.y = cvt_pk_bf16(v[2], v[3]); *(u32x2*)p = w; }
;     __device__ __forceinline__ void operator()(const f32x4 (&acc)[2][2][4][2], const Unit& u, int wr, int wc, int fr, int fq) const {
;         const int br = u.pm / 66, pm = u.pm - br * 66, pn = u.pn & 3;
;         if (br > 0) asm volatile("s_waitcnt vmcnt(0)" ::: "memory");
; #pragma unroll
;         for (int ai = 0; ai < 2; ++ai)
; #pragma unroll
;             for (int m = 0; m < 4; ++m) { const int row = pm * 256 + ai * 128 + wr * 64 + m * 16 + fr;
; #pragma unroll
;                 for (int bj = 0; bj < 2; ++bj)
; #pragma unroll
;                     for (int n = 0; n < 2; ++n) { const int col = pn * 256 + bj * 128 + wc * 32 + 8 * fq + 4 * n; const f32x4 v = acc[ai][bj][m][n];
;                         const f32x4 g = ld_bf4(GT + (size_t)row * 3072 + br * 1024 + col);
;                         bf16_t* mp = M16 + (size_t)row * 1024 + col;
;                         if (br == 0) st_bf4(mp, g * v); else st_bf4(mp, ld_bf4(mp) + g * v); } }
	v_lshlrev_b32_e32 v142, 16, v206
	v_and_b32_e32 v143, 0xffff0000, v206
	v_lshlrev_b32_e32 v144, 16, v207
	v_and_b32_e32 v145, 0xffff0000, v207
	v_max_f32_e32 v142, 0x2b800000, v142
	v_max_f32_e32 v143, 0x2b800000, v143
	v_max_f32_e32 v144, 0x2b800000, v144
	v_max_f32_e32 v145, 0x2b800000, v145
	v_pk_mul_f32 v[110:111], v[110:111], v[142:143]
	v_pk_mul_f32 v[112:113], v[112:113], v[144:145]
	v_cvt_pk_bf16_f32 v206, v110, v111
	v_cvt_pk_bf16_f32 v207, v112, v113
	v_lshlrev_b32_e32 v142, 16, v208
	v_and_b32_e32 v143, 0xffff0000, v208
	v_lshlrev_b32_e32 v144, 16, v209
	v_and_b32_e32 v145, 0xffff0000, v209
	v_max_f32_e32 v142, 0x2b800000, v142
	v_max_f32_e32 v143, 0x2b800000, v143
	v_max_f32_e32 v144, 0x2b800000, v144
	v_max_f32_e32 v145, 0x2b800000, v145
	v_pk_mul_f32 v[106:107], v[106:107], v[142:143]
	v_pk_mul_f32 v[108:109], v[108:109], v[144:145]
	v_cvt_pk_bf16_f32 v208, v106, v107
	v_cvt_pk_bf16_f32 v209, v108, v109
	v_lshlrev_b32_e32 v142, 16, v210
	v_and_b32_e32 v143, 0xffff0000, v210
	v_lshlrev_b32_e32 v144, 16, v211
	v_and_b32_e32 v145, 0xffff0000, v211
	v_max_f32_e32 v142, 0x2b800000, v142
	v_max_f32_e32 v143, 0x2b800000, v143
	v_max_f32_e32 v144, 0x2b800000, v144
	v_max_f32_e32 v145, 0x2b800000, v145
	v_pk_mul_f32 v[102:103], v[102:103], v[142:143]
	v_pk_mul_f32 v[104:105], v[104:105], v[144:145]
	v_cvt_pk_bf16_f32 v210, v102, v103
	v_cvt_pk_bf16_f32 v211, v104, v105
	v_lshlrev_b32_e32 v142, 16, v212
	v_and_b32_e32 v143, 0xffff0000, v212
	v_lshlrev_b32_e32 v144, 16, v213
	v_and_b32_e32 v145, 0xffff0000, v213
	v_max_f32_e32 v142, 0x2b800000, v142
	v_max_f32_e32 v143, 0x2b800000, v143
	v_max_f32_e32 v144, 0x2b800000, v144
	v_max_f32_e32 v145, 0x2b800000, v145
	v_pk_mul_f32 v[98:99], v[98:99], v[142:143]
	v_pk_mul_f32 v[100:101], v[100:101], v[144:145]
	v_cvt_pk_bf16_f32 v212, v98, v99
	v_cvt_pk_bf16_f32 v213, v100, v101
	global_store_dwordx4 v187, v[206:209], s[88:89]
	global_store_dwordx4 v187, v[210:213], s[88:89] offset:256
	s_waitcnt vmcnt(14)
	v_lshlrev_b32_e32 v142, 16, v214
	v_and_b32_e32 v143, 0xffff0000, v214
	v_lshlrev_b32_e32 v144, 16, v215
	v_and_b32_e32 v145, 0xffff0000, v215
	v_max_f32_e32 v142, 0x2b800000, v142
	v_max_f32_e32 v143, 0x2b800000, v143
	v_max_f32_e32 v144, 0x2b800000, v144
	v_max_f32_e32 v145, 0x2b800000, v145
	v_pk_mul_f32 v[92:93], v[92:93], v[142:143]
	v_pk_mul_f32 v[94:95], v[94:95], v[144:145]
	v_cvt_pk_bf16_f32 v214, v92, v93
	v_cvt_pk_bf16_f32 v215, v94, v95
	v_lshlrev_b32_e32 v142, 16, v216
	v_and_b32_e32 v143, 0xffff0000, v216
	v_lshlrev_b32_e32 v144, 16, v217
	v_and_b32_e32 v145, 0xffff0000, v217
	v_max_f32_e32 v142, 0x2b800000, v142
	v_max_f32_e32 v143, 0x2b800000, v143
	v_max_f32_e32 v144, 0x2b800000, v144
	v_max_f32_e32 v145, 0x2b800000, v145
	v_pk_mul_f32 v[88:89], v[88:89], v[142:143]
	v_pk_mul_f32 v[90:91], v[90:91], v[144:145]
	v_cvt_pk_bf16_f32 v216, v88, v89
	v_cvt_pk_bf16_f32 v217, v90, v91
	v_lshlrev_b32_e32 v142, 16, v218
	v_and_b32_e32 v143, 0xffff0000, v218
	v_lshlrev_b32_e32 v144, 16, v219
	v_and_b32_e32 v145, 0xffff0000, v219
	v_max_f32_e32 v142, 0x2b800000, v142
	v_max_f32_e32 v143, 0x2b800000, v143
	v_max_f32_e32 v144, 0x2b800000, v144
	v_max_f32_e32 v145, 0x2b800000, v145
	v_pk_mul_f32 v[84:85], v[84:85], v[142:143]
	v_pk_mul_f32 v[86:87], v[86:87], v[144:145]
	v_cvt_pk_bf16_f32 v218, v84, v85
	v_cvt_pk_bf16_f32 v219, v86, v87
	v_lshlrev_b32_e32 v142, 16, v220
	v_and_b32_e32 v143, 0xffff0000, v220
	v_lshlrev_b32_e32 v144, 16, v221
	v_and_b32_e32 v145, 0xffff0000, v221
	v_max_f32_e32 v142, 0x2b800000, v142
	v_max_f32_e32 v143, 0x2b800000, v143
	v_max_f32_e32 v144, 0x2b800000, v144
	v_max_f32_e32 v145, 0x2b800000, v145
	v_pk_mul_f32 v[80:81], v[80:81], v[142:143]
	v_pk_mul_f32 v[82:83], v[82:83], v[144:145]
	v_cvt_pk_bf16_f32 v220, v80, v81
	v_cvt_pk_bf16_f32 v221, v82, v83
	global_store_dwordx4 v188, v[214:217], s[88:89]
	global_store_dwordx4 v188, v[218:221], s[88:89] offset:256
	s_waitcnt vmcnt(14)
	v_lshlrev_b32_e32 v142, 16, v222
	v_and_b32_e32 v143, 0xffff0000, v222
	v_lshlrev_b32_e32 v144, 16, v223
	v_and_b32_e32 v145, 0xffff0000, v223
	v_max_f32_e32 v142, 0x2b800000, v142
	v_max_f32_e32 v143, 0x2b800000, v143
	v_max_f32_e32 v144, 0x2b800000, v144
	v_max_f32_e32 v145, 0x2b800000, v145
	v_pk_mul_f32 v[76:77], v[76:77], v[142:143]
	v_pk_mul_f32 v[78:79], v[78:79], v[144:145]
	v_cvt_pk_bf16_f32 v222, v76, v77
	v_cvt_pk_bf16_f32 v223, v78, v79
	v_lshlrev_b32_e32 v142, 16, v224
	v_and_b32_e32 v143, 0xffff0000, v224
	v_lshlrev_b32_e32 v144, 16, v225
	v_and_b32_e32 v145, 0xffff0000, v225
	v_max_f32_e32 v142, 0x2b800000, v142
	v_max_f32_e32 v143, 0x2b800000, v143
	v_max_f32_e32 v144, 0x2b800000, v144
	v_max_f32_e32 v145, 0x2b800000, v145
	v_pk_mul_f32 v[72:73], v[72:73], v[142:143]
	v_pk_mul_f32 v[74:75], v[74:75], v[144:145]
	v_cvt_pk_bf16_f32 v224, v72, v73
	v_cvt_pk_bf16_f32 v225, v74, v75
	v_lshlrev_b32_e32 v142, 16, v226
	v_and_b32_e32 v143, 0xffff0000, v226
	v_lshlrev_b32_e32 v144, 16, v227
	v_and_b32_e32 v145, 0xffff0000, v227
	v_max_f32_e32 v142, 0x2b800000, v142
	v_max_f32_e32 v143, 0x2b800000, v143
	v_max_f32_e32 v144, 0x2b800000, v144
	v_max_f32_e32 v145, 0x2b800000, v145
	v_pk_mul_f32 v[68:69], v[68:69], v[142:143]
	v_pk_mul_f32 v[70:71], v[70:71], v[144:145]
	v_cvt_pk_bf16_f32 v226, v68, v69
	v_cvt_pk_bf16_f32 v227, v70, v71
	v_lshlrev_b32_e32 v142, 16, v228
	v_and_b32_e32 v143, 0xffff0000, v228
	v_lshlrev_b32_e32 v144, 16, v229
	v_and_b32_e32 v145, 0xffff0000, v229
	v_max_f32_e32 v142, 0x2b800000, v142
	v_max_f32_e32 v143, 0x2b800000, v143
	v_max_f32_e32 v144, 0x2b800000, v144
	v_max_f32_e32 v145, 0x2b800000, v145
	v_pk_mul_f32 v[64:65], v[64:65], v[142:143]
	v_pk_mul_f32 v[66:67], v[66:67], v[144:145]
	v_cvt_pk_bf16_f32 v228, v64, v65
	v_cvt_pk_bf16_f32 v229, v66, v67
	global_store_dwordx4 v189, v[222:225], s[88:89]
	global_store_dwordx4 v189, v[226:229], s[88:89] offset:256
	s_waitcnt vmcnt(14)
; __device__ __forceinline__ f32x4 ld_bf4(const bf16_t* p) { const u32x2 w = *(const u32x2*)p; f32x4 r; r[0] = __uint_as_float(w.x << 16); r[1] = __uint_as_float(w.x & 0xffff0000u); r[2] = __uint_as_float(w.y << 16); r[3] = __uint_as_float(w.y & 0xffff0000u); return r; }
; __device__ __forceinline__ void st_bf4(bf16_t* p, const f32x4 v) { u32x2 w; w.x = cvt_pk_bf16(v[0], v[1]); w.y = cvt_pk_bf16(v[2], v[3]); *(u32x2*)p = w; }
;     __device__ __forceinline__ void operator()(const f32x4 (&acc)[2][2][4][2], const Unit& u, int wr, int wc, int fr, int fq) const {
;         const int br = u.pm / 66, pm = u.pm - br * 66, pn = u.pn & 3;
;         if (br > 0) asm volatile("s_waitcnt vmcnt(0)" ::: "memory");
; #pragma unroll
;         for (int ai = 0; ai < 2; ++ai)
; #pragma unroll
;             for (int m = 0; m < 4; ++m) { const int row = pm * 256 + ai * 128 + wr * 64 + m * 16 + fr;
; #pragma unroll
;                 for (int bj = 0; bj < 2; ++bj)
; #pragma unroll
;                     for (int n = 0; n < 2; ++n) { const int col = pn * 256 + bj * 128 + wc * 32 + 8 * fq + 4 * n; const f32x4 v = acc[ai][bj][m][n];
;                         const f32x4 g = ld_bf4(GT + (size_t)row * 3072 + br * 1024 + col);
;                         bf16_t* mp = M16 + (size_t)row * 1024 + col;
;                         if (br == 0) st_bf4(mp, g * v); else st_bf4(mp, ld_bf4(mp) + g * v); } }
	v_lshlrev_b32_e32 v142, 16, v230
	v_and_b32_e32 v143, 0xffff0000, v230
	v_lshlrev_b32_e32 v144, 16, v231
	v_and_b32_e32 v145, 0xffff0000, v231
	v_max_f32_e32 v142, 0x2b800000, v142
	v_max_f32_e32 v143, 0x2b800000, v143
	v_max_f32_e32 v144, 0x2b800000, v144
	v_max_f32_e32 v145, 0x2b800000, v145
	v_pk_mul_f32 v[60:61], v[60:61], v[142:143]
	v_pk_mul_f32 v[62:63], v[62:63], v[144:145]
	v_cvt_pk_bf16_f32 v230, v60, v61
	v_cvt_pk_bf16_f32 v231, v62, v63
	v_lshlrev_b32_e32 v142, 16, v232
	v_and_b32_e32 v143, 0xffff0000, v232
	v_lshlrev_b32_e32 v144, 16, v233
	v_and_b32_e32 v145, 0xffff0000, v233
	v_max_f32_e32 v142, 0x2b800000, v142
	v_max_f32_e32 v143, 0x2b800000, v143
	v_max_f32_e32 v144, 0x2b800000, v144
	v_max_f32_e32 v145, 0x2b800000, v145
	v_pk_mul_f32 v[56:57], v[56:57], v[142:143]
	v_pk_mul_f32 v[58:59], v[58:59], v[144:145]
	v_cvt_pk_bf16_f32 v232, v56, v57
	v_cvt_pk_bf16_f32 v233, v58, v59
	v_lshlrev_b32_e32 v142, 16, v234
	v_and_b32_e32 v143, 0xffff0000, v234
	v_lshlrev_b32_e32 v144, 16, v235
	v_and_b32_e32 v145, 0xffff0000, v235
	v_max_f32_e32 v142, 0x2b800000, v142
	v_max_f32_e32 v143, 0x2b800000, v143
	v_max_f32_e32 v144, 0x2b800000, v144
	v_max_f32_e32 v145, 0x2b800000, v145
	v_pk_mul_f32 v[52:53], v[52:53], v[142:143]
	v_pk_mul_f32 v[54:55], v[54:55], v[144:145]
	v_cvt_pk_bf16_f32 v234, v52, v53
	v_cvt_pk_bf16_f32 v235, v54, v55
	v_lshlrev_b32_e32 v142, 16, v236
	v_and_b32_e32 v143, 0xffff0000, v236
	v_lshlrev_b32_e32 v144, 16, v237
	v_and_b32_e32 v145, 0xffff0000, v237
	v_max_f32_e32 v142, 0x2b800000, v142
	v_max_f32_e32 v143, 0x2b800000, v143
	v_max_f32_e32 v144, 0x2b800000, v144
	v_max_f32_e32 v145, 0x2b800000, v145
	v_pk_mul_f32 v[48:49], v[48:49], v[142:143]
	v_pk_mul_f32 v[50:51], v[50:51], v[144:145]
	v_cvt_pk_bf16_f32 v236, v48, v49
	v_cvt_pk_bf16_f32 v237, v50, v51
	global_store_dwordx4 v190, v[230:233], s[88:89]
	global_store_dwordx4 v190, v[234:237], s[88:89] offset:256
	s_waitcnt vmcnt(14)
	v_lshlrev_b32_e32 v142, 16, v238
	v_and_b32_e32 v143, 0xffff0000, v238
	v_lshlrev_b32_e32 v144, 16, v239
	v_and_b32_e32 v145, 0xffff0000, v239
	v_max_f32_e32 v142, 0x2b800000, v142
	v_max_f32_e32 v143, 0x2b800000, v143
	v_max_f32_e32 v144, 0x2b800000, v144
	v_max_f32_e32 v145, 0x2b800000, v145
	v_pk_mul_f32 v[44:45], v[44:45], v[142:143]
	v_pk_mul_f32 v[46:47], v[46:47], v[144:145]
	v_cvt_pk_bf16_f32 v238, v44, v45
	v_cvt_pk_bf16_f32 v239, v46, v47
	v_lshlrev_b32_e32 v142, 16, v240
	v_and_b32_e32 v143, 0xffff0000, v240
	v_lshlrev_b32_e32 v144, 16, v241
	v_and_b32_e32 v145, 0xffff0000, v241
	v_max_f32_e32 v142, 0x2b800000, v142
	v_max_f32_e32 v143, 0x2b800000, v143
	v_max_f32_e32 v144, 0x2b800000, v144
	v_max_f32_e32 v145, 0x2b800000, v145
	v_pk_mul_f32 v[40:41], v[40:41], v[142:143]
	v_pk_mul_f32 v[42:43], v[42:43], v[144:145]
	v_cvt_pk_bf16_f32 v240, v40, v41
	v_cvt_pk_bf16_f32 v241, v42, v43
	v_lshlrev_b32_e32 v142, 16, v242
	v_and_b32_e32 v143, 0xffff0000, v242
	v_lshlrev_b32_e32 v144, 16, v243
	v_and_b32_e32 v145, 0xffff0000, v243
	v_max_f32_e32 v142, 0x2b800000, v142
	v_max_f32_e32 v143, 0x2b800000, v143
	v_max_f32_e32 v144, 0x2b800000, v144
	v_max_f32_e32 v145, 0x2b800000, v145
	v_pk_mul_f32 v[36:37], v[36:37], v[142:143]
	v_pk_mul_f32 v[38:39], v[38:39], v[144:145]
	v_cvt_pk_bf16_f32 v242, v36, v37
	v_cvt_pk_bf16_f32 v243, v38, v39
	v_lshlrev_b32_e32 v142, 16, v244
	v_and_b32_e32 v143, 0xffff0000, v244
	v_lshlrev_b32_e32 v144, 16, v245
	v_and_b32_e32 v145, 0xffff0000, v245
	v_max_f32_e32 v142, 0x2b800000, v142
	v_max_f32_e32 v143, 0x2b800000, v143
	v_max_f32_e32 v144, 0x2b800000, v144
	v_max_f32_e32 v145, 0x2b800000, v145
	v_pk_mul_f32 v[32:33], v[32:33], v[142:143]
	v_pk_mul_f32 v[34:35], v[34:35], v[144:145]
	v_cvt_pk_bf16_f32 v244, v32, v33
	v_cvt_pk_bf16_f32 v245, v34, v35
	global_store_dwordx4 v191, v[238:241], s[88:89]
	global_store_dwordx4 v191, v[242:245], s[88:89] offset:256
	s_waitcnt vmcnt(14)
; __device__ __forceinline__ f32x4 ld_bf4(const bf16_t* p) { const u32x2 w = *(const u32x2*)p; f32x4 r; r[0] = __uint_as_float(w.x << 16); r[1] = __uint_as_float(w.x & 0xffff0000u); r[2] = __uint_as_float(w.y << 16); r[3] = __uint_as_float(w.y & 0xffff0000u); return r; }
; __device__ __forceinline__ void st_bf4(bf16_t* p, const f32x4 v) { u32x2 w; w.x = cvt_pk_bf16(v[0], v[1]); w.y = cvt_pk_bf16(v[2], v[3]); *(u32x2*)p = w; }
;     __device__ __forceinline__ void operator()(const f32x4 (&acc)[2][2][4][2], const Unit& u, int wr, int wc, int fr, int fq) const {
;         const int br = u.pm / 66, pm = u.pm - br * 66, pn = u.pn & 3;
;         if (br > 0) asm volatile("s_waitcnt vmcnt(0)" ::: "memory");
; #pragma unroll
;         for (int ai = 0; ai < 2; ++ai)
; #pragma unroll
;             for (int m = 0; m < 4; ++m) { const int row = pm * 256 + ai * 128 + wr * 64 + m * 16 + fr;
; #pragma unroll
;                 for (int bj = 0; bj < 2; ++bj)
; #pragma unroll
;                     for (int n = 0; n < 2; ++n) { const int col = pn * 256 + bj * 128 + wc * 32 + 8 * fq + 4 * n; const f32x4 v = acc[ai][bj][m][n];
;                         const f32x4 g = ld_bf4(GT + (size_t)row * 3072 + br * 1024 + col);
;                         bf16_t* mp = M16 + (size_t)row * 1024 + col;
;                         if (br == 0) st_bf4(mp, g * v); else st_bf4(mp, ld_bf4(mp) + g * v); } }
;     }
	v_lshlrev_b32_e32 v142, 16, v246
	v_and_b32_e32 v143, 0xffff0000, v246
	v_lshlrev_b32_e32 v144, 16, v247
	v_and_b32_e32 v145, 0xffff0000, v247
	v_max_f32_e32 v142, 0x2b800000, v142
	v_max_f32_e32 v143, 0x2b800000, v143
	v_max_f32_e32 v144, 0x2b800000, v144
	v_max_f32_e32 v145, 0x2b800000, v145
	v_pk_mul_f32 v[28:29], v[28:29], v[142:143]
	v_pk_mul_f32 v[30:31], v[30:31], v[144:145]
	v_cvt_pk_bf16_f32 v246, v28, v29
	v_cvt_pk_bf16_f32 v247, v30, v31
	v_lshlrev_b32_e32 v142, 16, v248
	v_and_b32_e32 v143, 0xffff0000, v248
	v_lshlrev_b32_e32 v144, 16, v249
	v_and_b32_e32 v145, 0xffff0000, v249
	v_max_f32_e32 v142, 0x2b800000, v142
	v_max_f32_e32 v143, 0x2b800000, v143
	v_max_f32_e32 v144, 0x2b800000, v144
	v_max_f32_e32 v145, 0x2b800000, v145
	v_pk_mul_f32 v[24:25], v[24:25], v[142:143]
	v_pk_mul_f32 v[26:27], v[26:27], v[144:145]
	v_cvt_pk_bf16_f32 v248, v24, v25
	v_cvt_pk_bf16_f32 v249, v26, v27
	v_lshlrev_b32_e32 v142, 16, v250
	v_and_b32_e32 v143, 0xffff0000, v250
	v_lshlrev_b32_e32 v144, 16, v251
	v_and_b32_e32 v145, 0xffff0000, v251
	v_max_f32_e32 v142, 0x2b800000, v142
	v_max_f32_e32 v143, 0x2b800000, v143
	v_max_f32_e32 v144, 0x2b800000, v144
	v_max_f32_e32 v145, 0x2b800000, v145
	v_pk_mul_f32 v[20:21], v[20:21], v[142:143]
	v_pk_mul_f32 v[22:23], v[22:23], v[144:145]
	v_cvt_pk_bf16_f32 v250, v20, v21
	v_cvt_pk_bf16_f32 v251, v22, v23
	v_lshlrev_b32_e32 v142, 16, v252
	v_and_b32_e32 v143, 0xffff0000, v252
	v_lshlrev_b32_e32 v144, 16, v253
	v_and_b32_e32 v145, 0xffff0000, v253
	v_max_f32_e32 v142, 0x2b800000, v142
	v_max_f32_e32 v143, 0x2b800000, v143
	v_max_f32_e32 v144, 0x2b800000, v144
	v_max_f32_e32 v145, 0x2b800000, v145
	v_pk_mul_f32 v[16:17], v[16:17], v[142:143]
	v_pk_mul_f32 v[18:19], v[18:19], v[144:145]
	v_cvt_pk_bf16_f32 v252, v16, v17
	v_cvt_pk_bf16_f32 v253, v18, v19
	global_store_dwordx4 v192, v[246:249], s[88:89]
	global_store_dwordx4 v192, v[250:253], s[88:89] offset:256
	s_waitcnt vmcnt(14)
	v_lshlrev_b32_e32 v142, 16, v182
	v_and_b32_e32 v143, 0xffff0000, v182
	v_lshlrev_b32_e32 v144, 16, v183
	v_and_b32_e32 v145, 0xffff0000, v183
	v_max_f32_e32 v142, 0x2b800000, v142
	v_max_f32_e32 v143, 0x2b800000, v143
	v_max_f32_e32 v144, 0x2b800000, v144
	v_max_f32_e32 v145, 0x2b800000, v145
	v_pk_mul_f32 v[12:13], v[12:13], v[142:143]
	v_pk_mul_f32 v[14:15], v[14:15], v[144:145]
	v_cvt_pk_bf16_f32 v182, v12, v13
	v_cvt_pk_bf16_f32 v183, v14, v15
	v_lshlrev_b32_e32 v142, 16, v184
	v_and_b32_e32 v143, 0xffff0000, v184
	v_lshlrev_b32_e32 v144, 16, v185
	v_and_b32_e32 v145, 0xffff0000, v185
	v_max_f32_e32 v142, 0x2b800000, v142
	v_max_f32_e32 v143, 0x2b800000, v143
	v_max_f32_e32 v144, 0x2b800000, v144
	v_max_f32_e32 v145, 0x2b800000, v145
	v_pk_mul_f32 v[8:9], v[8:9], v[142:143]
	v_pk_mul_f32 v[10:11], v[10:11], v[144:145]
	v_cvt_pk_bf16_f32 v184, v8, v9
	v_cvt_pk_bf16_f32 v185, v10, v11
	v_lshlrev_b32_e32 v142, 16, v150
	v_and_b32_e32 v143, 0xffff0000, v150
	v_lshlrev_b32_e32 v144, 16, v151
	v_and_b32_e32 v145, 0xffff0000, v151
	v_max_f32_e32 v142, 0x2b800000, v142
	v_max_f32_e32 v143, 0x2b800000, v143
	v_max_f32_e32 v144, 0x2b800000, v144
	v_max_f32_e32 v145, 0x2b800000, v145
	v_pk_mul_f32 v[4:5], v[4:5], v[142:143]
	v_pk_mul_f32 v[6:7], v[6:7], v[144:145]
	v_cvt_pk_bf16_f32 v150, v4, v5
	v_cvt_pk_bf16_f32 v151, v6, v7
	v_lshlrev_b32_e32 v142, 16, v152
	v_and_b32_e32 v143, 0xffff0000, v152
	v_lshlrev_b32_e32 v144, 16, v153
	v_and_b32_e32 v145, 0xffff0000, v153
	v_max_f32_e32 v142, 0x2b800000, v142
	v_max_f32_e32 v143, 0x2b800000, v143
	v_max_f32_e32 v144, 0x2b800000, v144
	v_max_f32_e32 v145, 0x2b800000, v145
	v_pk_mul_f32 v[0:1], v[0:1], v[142:143]
	v_pk_mul_f32 v[2:3], v[2:3], v[144:145]
	v_cvt_pk_bf16_f32 v152, v0, v1
	v_cvt_pk_bf16_f32 v153, v2, v3
	global_store_dwordx4 v193, v[182:185], s[88:89]
	global_store_dwordx4 v193, v[150:153], s[88:89] offset:256
